# first K-iteration of each non-first tile in P1/P9/P3 lets the previous tile's epilogue stores stay outstanding at the first two counted vmcnt waits (vmcnt 16/24 instead of 8), on top of lean P3 epilog
# baseline (speedup 1.0000x reference)
; #define PG8_STAGE(bufoff, gbase, voff) do { _Pragma("unroll") for (int _i = 0; _i < 2; ++_i) \
;         __builtin_amdgcn_global_load_lds((const unsigned*)((const char*)(gbase) + (voff)[_i]), (PG8_LAS unsigned*)(lds + (bufoff) + ldsw + _i * 8192), 16, 0, 0); } while (0)
; #define PG8_LDA(dst, b, h) do { _Pragma("unroll") for (int m = 0; m < 4; ++m) _Pragma("unroll") for (int k = 0; k < 2; ++k) dst[m][k] = *(const PG8_LAS bf16x8*)(lds + PG8_SA(b, h) + aoff + m * 2048 + k * 1024); } while (0)
; #define PG8_LDB(dst, b, h) do { _Pragma("unroll") for (int n = 0; n < 2; ++n) _Pragma("unroll") for (int k = 0; k < 2; ++k) dst[n][k] = *(const PG8_LAS bf16x8*)(lds + PG8_SB(b, h) + boff + n * 2048 + k * 1024); } while (0)
; #define PG8_MMA(ai, bj, At, Bt) do { __builtin_amdgcn_s_setprio(1); _Pragma("unroll") for (int m = 0; m < 4; ++m) _Pragma("unroll") for (int n = 0; n < 2; ++n) _Pragma("unroll") for (int k = 0; k < 2; ++k) \
;         acc[ai][bj][m][n] = __builtin_amdgcn_mfma_f32_16x16x32_bf16(Bt[n][k], At[m][k], acc[ai][bj][m][n], 0, 0, 0); __builtin_amdgcn_s_setprio(0); } while (0)
; #define PG8_WAIT_V(n) asm volatile("s_waitcnt vmcnt(" #n ")" ::: "memory")
; #define PG8_WAIT_L(n) asm volatile("s_waitcnt lgkmcnt(" #n ")" ::: "memory")
; #define PG8_BAR __builtin_amdgcn_s_barrier()
; template <class Epi, bool ALIGN_EPI, bool ABLK = false>
; __device__ __forceinline__ void gemm_phase(PG8_LAS unsigned char* lds, const Gemm g, const StaticOrder& S, const Epi& E) {
;     ...
;         for (int t = 0; t < nt; t += 2) {
;             const bool last = (t == nt - 2);
;             const char* a1 = cA + (size_t)(t + 1) * kstepA;
;             const char* a2 = last ? nA : cA + (size_t)(t + 2) * kstepA; const char* b2 = last ? nB : cB + (size_t)(t + 2) * kstepB;
;             const char* a3 = a2 + kstepA; const char* b3 = b2 + kstepB;
;             PG8_LDB(B0, 0, 0); PG8_LDB(B1, 0, 1); PG8_SCHED; PG8_LDA(At, 0, 0); PG8_STAGE(PG8_SA(1, 1), a1 + hstepA, voffA);
;             PG8_WAIT_V(8); PG8_WAIT_L(0); PG8_BAR; PG8_MMA(0, 0, At, B0); PG8_MMA(0, 1, At, B1); PG8_BAR; PG8_SCHED;
;             PG8_LDA(At, 0, 1); PG8_STAGE(PG8_SB(0, 0), b2, voffB); PG8_STAGE(PG8_SB(0, 1), b2 + hstepB, voffB); PG8_STAGE(PG8_SA(0, 0), a2, voffA);
;             PG8_WAIT_V(8); PG8_WAIT_L(0); PG8_BAR; PG8_MMA(1, 0, At, B0); PG8_MMA(1, 1, At, B1); PG8_BAR; PG8_SCHED;
.LBB0_402:
	ds_read_b128 v[132:135], v251
	ds_read_b128 v[136:139], v251 offset:1024
	ds_read_b128 v[140:143], v251 offset:2048
	ds_read_b128 v[186:189], v251 offset:3072
	ds_read_b128 v[190:193], v251 offset:16384
	ds_read_b128 v[194:197], v251 offset:17408
	ds_read_b128 v[198:201], v251 offset:18432
	ds_read_b128 v[202:205], v251 offset:19456
	s_add_u32 s48, s24, s46
	s_addc_u32 s49, s25, s47
	s_cmp_eq_u32 s70, 12
	s_cselect_b32 s85, s41, s49
	s_cselect_b32 s84, s66, s48
	s_cselect_b32 s49, s39, s69
	s_cselect_b32 s48, s67, s68
	s_mov_b64 s[74:75], 0xc000
	s_add_i32 m0, s55, 0xc000
	s_mov_b64 s[74:75], 0xe000
	ds_read_b128 v[206:209], v183
	ds_read_b128 v[210:213], v183 offset:1024
	ds_read_b128 v[214:217], v183 offset:2048
	ds_read_b128 v[218:221], v183 offset:3072
	ds_read_b128 v[222:225], v183 offset:4096
	ds_read_b128 v[226:229], v183 offset:5120
	ds_read_b128 v[230:233], v183 offset:6144
	ds_read_b128 v[234:237], v183 offset:7168
	global_load_lds_dwordx4 v249, s[82:83]
	s_add_i32 m0, s55, 0xe000
	s_nop 0
	global_load_lds_dwordx4 v250, s[82:83]
	s_cmp_lg_u32 s70, -2
	s_cbranch_scc1 .Lrw_p1_0_n
	s_cmp_eq_u32 s60, 0
	s_cbranch_scc1 .Lrw_p1_0_n
	s_waitcnt vmcnt(16)
	s_branch .Lrw_p1_0_d
.Lrw_p1_0_n:
	s_waitcnt vmcnt(8)
.Lrw_p1_0_d:
	s_waitcnt lgkmcnt(0)
	s_barrier
	s_setprio 1
	s_waitcnt lgkmcnt(0)
	v_mfma_f32_16x16x32_bf16 v[126:129], v[132:135], v[206:209], v[126:129]
	v_mfma_f32_16x16x32_bf16 v[122:125], v[140:143], v[206:209], v[122:125]
	v_mfma_f32_16x16x32_bf16 v[118:121], v[132:135], v[214:217], v[118:121]
	v_mfma_f32_16x16x32_bf16 v[114:117], v[140:143], v[214:217], v[114:117]
	v_mfma_f32_16x16x32_bf16 v[110:113], v[132:135], v[222:225], v[110:113]
	v_mfma_f32_16x16x32_bf16 v[106:109], v[140:143], v[222:225], v[106:109]
	v_mfma_f32_16x16x32_bf16 v[102:105], v[132:135], v[230:233], v[102:105]
	v_mfma_f32_16x16x32_bf16 v[98:101], v[140:143], v[230:233], v[98:101]
	v_mfma_f32_16x16x32_bf16 v[126:129], v[136:139], v[210:213], v[126:129]
	v_mfma_f32_16x16x32_bf16 v[122:125], v[186:189], v[210:213], v[122:125]
	v_mfma_f32_16x16x32_bf16 v[118:121], v[136:139], v[218:221], v[118:121]
	v_mfma_f32_16x16x32_bf16 v[114:117], v[186:189], v[218:221], v[114:117]
	v_mfma_f32_16x16x32_bf16 v[110:113], v[136:139], v[226:229], v[110:113]
	v_mfma_f32_16x16x32_bf16 v[106:109], v[186:189], v[226:229], v[106:109]
	v_mfma_f32_16x16x32_bf16 v[102:105], v[136:139], v[234:237], v[102:105]
	v_mfma_f32_16x16x32_bf16 v[98:101], v[186:189], v[234:237], v[98:101]
	s_setprio 0
	s_setprio 1
	v_mfma_f32_16x16x32_bf16 v[94:97], v[190:193], v[206:209], v[94:97]
	v_mfma_f32_16x16x32_bf16 v[90:93], v[198:201], v[206:209], v[90:93]
	v_mfma_f32_16x16x32_bf16 v[86:89], v[190:193], v[214:217], v[86:89]
	v_mfma_f32_16x16x32_bf16 v[82:85], v[198:201], v[214:217], v[82:85]
	v_mfma_f32_16x16x32_bf16 v[78:81], v[190:193], v[222:225], v[78:81]
	v_mfma_f32_16x16x32_bf16 v[74:77], v[198:201], v[222:225], v[74:77]
	v_mfma_f32_16x16x32_bf16 v[70:73], v[190:193], v[230:233], v[70:73]
	v_mfma_f32_16x16x32_bf16 v[66:69], v[198:201], v[230:233], v[66:69]
	v_mfma_f32_16x16x32_bf16 v[94:97], v[194:197], v[210:213], v[94:97]
	v_mfma_f32_16x16x32_bf16 v[90:93], v[202:205], v[210:213], v[90:93]
	v_mfma_f32_16x16x32_bf16 v[86:89], v[194:197], v[218:221], v[86:89]
	v_mfma_f32_16x16x32_bf16 v[82:85], v[202:205], v[218:221], v[82:85]
	v_mfma_f32_16x16x32_bf16 v[78:81], v[194:197], v[226:229], v[78:81]
	v_mfma_f32_16x16x32_bf16 v[74:77], v[202:205], v[226:229], v[74:77]
	v_mfma_f32_16x16x32_bf16 v[70:73], v[194:197], v[234:237], v[70:73]
	v_mfma_f32_16x16x32_bf16 v[66:69], v[202:205], v[234:237], v[66:69]
	s_setprio 0
	s_barrier
	s_add_i32 s71, s64, s9
	s_mov_b32 m0, s71
	ds_read_b128 v[206:209], v183 offset:16384
	ds_read_b128 v[210:213], v183 offset:17408
	ds_read_b128 v[214:217], v183 offset:18432
	ds_read_b128 v[218:221], v183 offset:19456
	ds_read_b128 v[222:225], v183 offset:20480
	ds_read_b128 v[226:229], v183 offset:21504
	ds_read_b128 v[230:233], v183 offset:22528
	ds_read_b128 v[234:237], v183 offset:23552
	global_load_lds_dwordx4 v148, s[48:49]
	s_add_i32 m0, s71, 0x2000
	s_add_u32 s74, s48, 0x40000
	s_addc_u32 s75, s49, 0
	s_add_i32 s71, s65, s9
	global_load_lds_dwordx4 v150, s[48:49]
	s_mov_b32 m0, s71
	s_nop 0
	global_load_lds_dwordx4 v148, s[74:75]
	s_add_i32 m0, s71, 0x2000
	s_nop 0
	global_load_lds_dwordx4 v150, s[74:75]
	s_mov_b32 m0, s55
	s_mov_b64 s[72:73], 0x2000
	global_load_lds_dwordx4 v146, s[84:85]
	s_mov_b32 m0, s56
	s_nop 0
	global_load_lds_dwordx4 v244, s[84:85]
	s_cmp_lg_u32 s70, -2
	s_cbranch_scc1 .Lrw_p1_1_n
	s_cmp_eq_u32 s60, 0
	s_cbranch_scc1 .Lrw_p1_1_n
	s_waitcnt vmcnt(16)
	s_branch .Lrw_p1_1_d

; #define PG8_STAGE(bufoff, gbase, voff) do { _Pragma("unroll") for (int _i = 0; _i < 2; ++_i) \
;         __builtin_amdgcn_global_load_lds((const unsigned*)((const char*)(gbase) + (voff)[_i]), (PG8_LAS unsigned*)(lds + (bufoff) + ldsw + _i * 8192), 16, 0, 0); } while (0)
; #define PG8_LDA(dst, b, h) do { _Pragma("unroll") for (int m = 0; m < 4; ++m) _Pragma("unroll") for (int k = 0; k < 2; ++k) dst[m][k] = *(const PG8_LAS bf16x8*)(lds + PG8_SA(b, h) + aoff + m * 2048 + k * 1024); } while (0)
; #define PG8_LDB(dst, b, h) do { _Pragma("unroll") for (int n = 0; n < 2; ++n) _Pragma("unroll") for (int k = 0; k < 2; ++k) dst[n][k] = *(const PG8_LAS bf16x8*)(lds + PG8_SB(b, h) + boff + n * 2048 + k * 1024); } while (0)
; #define PG8_MMA(ai, bj, At, Bt) do { __builtin_amdgcn_s_setprio(1); _Pragma("unroll") for (int m = 0; m < 4; ++m) _Pragma("unroll") for (int n = 0; n < 2; ++n) _Pragma("unroll") for (int k = 0; k < 2; ++k) \
;         acc[ai][bj][m][n] = __builtin_amdgcn_mfma_f32_16x16x32_bf16(Bt[n][k], At[m][k], acc[ai][bj][m][n], 0, 0, 0); __builtin_amdgcn_s_setprio(0); } while (0)
; #define PG8_WAIT_V(n) asm volatile("s_waitcnt vmcnt(" #n ")" ::: "memory")
; #define PG8_WAIT_L(n) asm volatile("s_waitcnt lgkmcnt(" #n ")" ::: "memory")
; #define PG8_BAR __builtin_amdgcn_s_barrier()
; #define PG8_SCHED __builtin_amdgcn_sched_barrier(0)
; template <class Epi, bool ALIGN_EPI, bool ABLK = false>
; __device__ __forceinline__ void gemm_phase(PG8_LAS unsigned char* lds, const Gemm g, const StaticOrder& S, const Epi& E) {
;     ...
;             PG8_WAIT_V(8); PG8_WAIT_L(0); PG8_BAR; PG8_MMA(0, 0, At, B0); PG8_MMA(0, 1, At, B1); PG8_BAR; PG8_SCHED;
;             PG8_LDA(At, 0, 1); PG8_STAGE(PG8_SB(0, 0), b2, voffB); PG8_STAGE(PG8_SB(0, 1), b2 + hstepB, voffB); PG8_STAGE(PG8_SA(0, 0), a2, voffA);
;             PG8_WAIT_V(8); PG8_WAIT_L(0); PG8_BAR; PG8_MMA(1, 0, At, B0); PG8_MMA(1, 1, At, B1); PG8_BAR; PG8_SCHED;
;             PG8_LDB(B0, 1, 0); PG8_LDB(B1, 1, 1); PG8_SCHED; PG8_LDA(At, 1, 0); PG8_STAGE(PG8_SA(0, 1), a2 + hstepA, voffA);
;             PG8_WAIT_V(8); PG8_WAIT_L(0); PG8_BAR; PG8_MMA(0, 0, At, B0); PG8_MMA(0, 1, At, B1); PG8_BAR; PG8_SCHED;
.Lrw_p1_1_d:
	s_waitcnt lgkmcnt(0)
	s_barrier
	s_setprio 1
	s_waitcnt lgkmcnt(0)
	v_mfma_f32_16x16x32_bf16 v[62:65], v[132:135], v[206:209], v[62:65]
	v_mfma_f32_16x16x32_bf16 v[58:61], v[140:143], v[206:209], v[58:61]
	v_mfma_f32_16x16x32_bf16 v[54:57], v[132:135], v[214:217], v[54:57]
	v_mfma_f32_16x16x32_bf16 v[50:53], v[140:143], v[214:217], v[50:53]
	v_mfma_f32_16x16x32_bf16 v[46:49], v[132:135], v[222:225], v[46:49]
	v_mfma_f32_16x16x32_bf16 v[42:45], v[140:143], v[222:225], v[42:45]
	v_mfma_f32_16x16x32_bf16 v[38:41], v[132:135], v[230:233], v[38:41]
	v_mfma_f32_16x16x32_bf16 v[34:37], v[140:143], v[230:233], v[34:37]
	v_mfma_f32_16x16x32_bf16 v[62:65], v[136:139], v[210:213], v[62:65]
	v_mfma_f32_16x16x32_bf16 v[58:61], v[186:189], v[210:213], v[58:61]
	v_mfma_f32_16x16x32_bf16 v[54:57], v[136:139], v[218:221], v[54:57]
	v_mfma_f32_16x16x32_bf16 v[50:53], v[186:189], v[218:221], v[50:53]
	v_mfma_f32_16x16x32_bf16 v[46:49], v[136:139], v[226:229], v[46:49]
	v_mfma_f32_16x16x32_bf16 v[42:45], v[186:189], v[226:229], v[42:45]
	v_mfma_f32_16x16x32_bf16 v[38:41], v[136:139], v[234:237], v[38:41]
	v_mfma_f32_16x16x32_bf16 v[34:37], v[186:189], v[234:237], v[34:37]
	s_setprio 0
	s_setprio 1
	v_mfma_f32_16x16x32_bf16 v[30:33], v[190:193], v[206:209], v[30:33]
	v_mfma_f32_16x16x32_bf16 v[26:29], v[198:201], v[206:209], v[26:29]
	v_mfma_f32_16x16x32_bf16 v[22:25], v[190:193], v[214:217], v[22:25]
	v_mfma_f32_16x16x32_bf16 v[18:21], v[198:201], v[214:217], v[18:21]
	v_mfma_f32_16x16x32_bf16 v[14:17], v[190:193], v[222:225], v[14:17]
	v_mfma_f32_16x16x32_bf16 v[10:13], v[198:201], v[222:225], v[10:13]
	v_mfma_f32_16x16x32_bf16 v[6:9], v[190:193], v[230:233], v[6:9]
	v_mfma_f32_16x16x32_bf16 v[2:5], v[198:201], v[230:233], v[2:5]
	v_mfma_f32_16x16x32_bf16 v[30:33], v[194:197], v[210:213], v[30:33]
	v_mfma_f32_16x16x32_bf16 v[26:29], v[202:205], v[210:213], v[26:29]
	v_mfma_f32_16x16x32_bf16 v[22:25], v[194:197], v[218:221], v[22:25]
	v_mfma_f32_16x16x32_bf16 v[18:21], v[202:205], v[218:221], v[18:21]
	v_mfma_f32_16x16x32_bf16 v[14:17], v[194:197], v[226:229], v[14:17]
	v_mfma_f32_16x16x32_bf16 v[10:13], v[202:205], v[226:229], v[10:13]
	v_mfma_f32_16x16x32_bf16 v[6:9], v[194:197], v[234:237], v[6:9]
	v_mfma_f32_16x16x32_bf16 v[2:5], v[202:205], v[234:237], v[2:5]
	s_setprio 0
	s_barrier
	s_add_i32 s71, 0, 0x18000
	s_add_i32 s74, 0, 0x1c000
	ds_read_b128 v[132:135], v251 offset:32768
	ds_read_b128 v[136:139], v251 offset:33792
	ds_read_b128 v[140:143], v251 offset:34816
	ds_read_b128 v[186:189], v251 offset:35840
	ds_read_b128 v[190:193], v251 offset:49152
	ds_read_b128 v[194:197], v251 offset:50176
	ds_read_b128 v[198:201], v251 offset:51200
	ds_read_b128 v[202:205], v251 offset:52224
	s_mov_b64 s[72:73], 0x4000
	s_mov_b32 m0, s57
	s_mov_b64 s[72:73], 0x6000
	ds_read_b128 v[206:209], v183 offset:32768
	ds_read_b128 v[210:213], v183 offset:33792
	ds_read_b128 v[214:217], v183 offset:34816
	ds_read_b128 v[218:221], v183 offset:35840
	ds_read_b128 v[222:225], v183 offset:36864
	ds_read_b128 v[226:229], v183 offset:37888
	ds_read_b128 v[230:233], v183 offset:38912
	ds_read_b128 v[234:237], v183 offset:39936
	global_load_lds_dwordx4 v245, s[84:85]
	s_mov_b32 m0, s58
	s_nop 0
	global_load_lds_dwordx4 v246, s[84:85]
	s_waitcnt vmcnt(8)
	s_waitcnt lgkmcnt(0)
	s_barrier
	s_setprio 1
	s_waitcnt lgkmcnt(0)
	v_mfma_f32_16x16x32_bf16 v[126:129], v[132:135], v[206:209], v[126:129]
	v_mfma_f32_16x16x32_bf16 v[122:125], v[140:143], v[206:209], v[122:125]
	v_mfma_f32_16x16x32_bf16 v[118:121], v[132:135], v[214:217], v[118:121]
	v_mfma_f32_16x16x32_bf16 v[114:117], v[140:143], v[214:217], v[114:117]
	v_mfma_f32_16x16x32_bf16 v[110:113], v[132:135], v[222:225], v[110:113]
	v_mfma_f32_16x16x32_bf16 v[106:109], v[140:143], v[222:225], v[106:109]
	v_mfma_f32_16x16x32_bf16 v[102:105], v[132:135], v[230:233], v[102:105]
	v_mfma_f32_16x16x32_bf16 v[98:101], v[140:143], v[230:233], v[98:101]
	v_mfma_f32_16x16x32_bf16 v[126:129], v[136:139], v[210:213], v[126:129]
	v_mfma_f32_16x16x32_bf16 v[122:125], v[186:189], v[210:213], v[122:125]
	v_mfma_f32_16x16x32_bf16 v[118:121], v[136:139], v[218:221], v[118:121]
	v_mfma_f32_16x16x32_bf16 v[114:117], v[186:189], v[218:221], v[114:117]
	v_mfma_f32_16x16x32_bf16 v[110:113], v[136:139], v[226:229], v[110:113]
	v_mfma_f32_16x16x32_bf16 v[106:109], v[186:189], v[226:229], v[106:109]
	v_mfma_f32_16x16x32_bf16 v[102:105], v[136:139], v[234:237], v[102:105]
	v_mfma_f32_16x16x32_bf16 v[98:101], v[186:189], v[234:237], v[98:101]
	s_setprio 0
	s_setprio 1
	v_mfma_f32_16x16x32_bf16 v[94:97], v[190:193], v[206:209], v[94:97]
	v_mfma_f32_16x16x32_bf16 v[90:93], v[198:201], v[206:209], v[90:93]
	v_mfma_f32_16x16x32_bf16 v[86:89], v[190:193], v[214:217], v[86:89]
	v_mfma_f32_16x16x32_bf16 v[82:85], v[198:201], v[214:217], v[82:85]
	v_mfma_f32_16x16x32_bf16 v[78:81], v[190:193], v[222:225], v[78:81]
	v_mfma_f32_16x16x32_bf16 v[74:77], v[198:201], v[222:225], v[74:77]
	v_mfma_f32_16x16x32_bf16 v[70:73], v[190:193], v[230:233], v[70:73]
	v_mfma_f32_16x16x32_bf16 v[66:69], v[198:201], v[230:233], v[66:69]
	v_mfma_f32_16x16x32_bf16 v[94:97], v[194:197], v[210:213], v[94:97]
	v_mfma_f32_16x16x32_bf16 v[90:93], v[202:205], v[210:213], v[90:93]
	v_mfma_f32_16x16x32_bf16 v[86:89], v[194:197], v[218:221], v[86:89]
	v_mfma_f32_16x16x32_bf16 v[82:85], v[202:205], v[218:221], v[82:85]
	v_mfma_f32_16x16x32_bf16 v[78:81], v[194:197], v[226:229], v[78:81]
	v_mfma_f32_16x16x32_bf16 v[74:77], v[202:205], v[226:229], v[74:77]
	v_mfma_f32_16x16x32_bf16 v[70:73], v[194:197], v[234:237], v[70:73]
	v_mfma_f32_16x16x32_bf16 v[66:69], v[202:205], v[234:237], v[66:69]
	s_setprio 0
	s_barrier
; #define PG8_STAGE(bufoff, gbase, voff) do { _Pragma("unroll") for (int _i = 0; _i < 2; ++_i) \
;         __builtin_amdgcn_global_load_lds((const unsigned*)((const char*)(gbase) + (voff)[_i]), (PG8_LAS unsigned*)(lds + (bufoff) + ldsw + _i * 8192), 16, 0, 0); } while (0)
; #define PG8_LDA(dst, b, h) do { _Pragma("unroll") for (int m = 0; m < 4; ++m) _Pragma("unroll") for (int k = 0; k < 2; ++k) dst[m][k] = *(const PG8_LAS bf16x8*)(lds + PG8_SA(b, h) + aoff + m * 2048 + k * 1024); } while (0)
; #define PG8_MMA(ai, bj, At, Bt) do { __builtin_amdgcn_s_setprio(1); _Pragma("unroll") for (int m = 0; m < 4; ++m) _Pragma("unroll") for (int n = 0; n < 2; ++n) _Pragma("unroll") for (int k = 0; k < 2; ++k) \
;         acc[ai][bj][m][n] = __builtin_amdgcn_mfma_f32_16x16x32_bf16(Bt[n][k], At[m][k], acc[ai][bj][m][n], 0, 0, 0); __builtin_amdgcn_s_setprio(0); } while (0)
; #define PG8_WAIT_V(n) asm volatile("s_waitcnt vmcnt(" #n ")" ::: "memory")
; #define PG8_WAIT_L(n) asm volatile("s_waitcnt lgkmcnt(" #n ")" ::: "memory")
; #define PG8_BAR __builtin_amdgcn_s_barrier()
; #define PG8_SCHED __builtin_amdgcn_sched_barrier(0)
; template <class Epi, bool ALIGN_EPI, bool ABLK = false>
; __device__ __forceinline__ void gemm_phase(PG8_LAS unsigned char* lds, const Gemm g, const StaticOrder& S, const Epi& E) {
;     ...
;             PG8_LDA(At, 1, 1); PG8_STAGE(PG8_SB(1, 0), b3, voffB); PG8_STAGE(PG8_SB(1, 1), b3 + hstepB, voffB); PG8_STAGE(PG8_SA(1, 0), a3, voffA);
;             PG8_WAIT_V(8); PG8_WAIT_L(0); PG8_BAR; PG8_MMA(1, 0, At, B0); PG8_MMA(1, 1, At, B1); PG8_BAR; PG8_SCHED;
;         }
	s_add_i32 s71, s71, s9
	s_add_u32 s86, s48, s28
	s_addc_u32 s87, s49, s29
	s_mov_b32 m0, s71
	ds_read_b128 v[206:209], v183 offset:49152
	ds_read_b128 v[210:213], v183 offset:50176
	ds_read_b128 v[214:217], v183 offset:51200
	ds_read_b128 v[218:221], v183 offset:52224
	ds_read_b128 v[222:225], v183 offset:53248
	ds_read_b128 v[226:229], v183 offset:54272
	ds_read_b128 v[230:233], v183 offset:55296
	ds_read_b128 v[234:237], v183 offset:56320
	global_load_lds_dwordx4 v148, s[86:87]
	s_add_i32 m0, s71, 0x2000
	s_add_u32 s48, s48, 0x40080
	s_addc_u32 s49, s49, 0
	s_add_i32 s71, s74, s9
	global_load_lds_dwordx4 v150, s[86:87]
	s_mov_b32 m0, s71
	s_nop 0
	global_load_lds_dwordx4 v148, s[48:49]
	s_add_i32 m0, s71, 0x2000
	s_nop 0
	global_load_lds_dwordx4 v150, s[48:49]
	s_mov_b32 m0, s59
	s_nop 0
	global_load_lds_dwordx4 v247, s[84:85]
	s_mov_b32 m0, s61
	s_nop 0
	global_load_lds_dwordx4 v248, s[84:85]
	s_waitcnt vmcnt(8)
	s_waitcnt lgkmcnt(0)
	s_barrier
	s_setprio 1
	s_waitcnt lgkmcnt(0)
	v_mfma_f32_16x16x32_bf16 v[62:65], v[132:135], v[206:209], v[62:65]
	v_mfma_f32_16x16x32_bf16 v[58:61], v[140:143], v[206:209], v[58:61]
	v_mfma_f32_16x16x32_bf16 v[54:57], v[132:135], v[214:217], v[54:57]
	v_mfma_f32_16x16x32_bf16 v[50:53], v[140:143], v[214:217], v[50:53]
	v_mfma_f32_16x16x32_bf16 v[46:49], v[132:135], v[222:225], v[46:49]
	v_mfma_f32_16x16x32_bf16 v[42:45], v[140:143], v[222:225], v[42:45]
	v_mfma_f32_16x16x32_bf16 v[38:41], v[132:135], v[230:233], v[38:41]
	v_mfma_f32_16x16x32_bf16 v[34:37], v[140:143], v[230:233], v[34:37]
	v_mfma_f32_16x16x32_bf16 v[62:65], v[136:139], v[210:213], v[62:65]
	v_mfma_f32_16x16x32_bf16 v[58:61], v[186:189], v[210:213], v[58:61]
	v_mfma_f32_16x16x32_bf16 v[54:57], v[136:139], v[218:221], v[54:57]
	v_mfma_f32_16x16x32_bf16 v[50:53], v[186:189], v[218:221], v[50:53]
	v_mfma_f32_16x16x32_bf16 v[46:49], v[136:139], v[226:229], v[46:49]
	v_mfma_f32_16x16x32_bf16 v[42:45], v[186:189], v[226:229], v[42:45]
	v_mfma_f32_16x16x32_bf16 v[38:41], v[136:139], v[234:237], v[38:41]
	v_mfma_f32_16x16x32_bf16 v[34:37], v[186:189], v[234:237], v[34:37]
	s_setprio 0
	s_setprio 1
	v_mfma_f32_16x16x32_bf16 v[30:33], v[190:193], v[206:209], v[30:33]
	v_mfma_f32_16x16x32_bf16 v[26:29], v[198:201], v[206:209], v[26:29]
	v_mfma_f32_16x16x32_bf16 v[22:25], v[190:193], v[214:217], v[22:25]
	v_mfma_f32_16x16x32_bf16 v[18:21], v[198:201], v[214:217], v[18:21]
	v_mfma_f32_16x16x32_bf16 v[14:17], v[190:193], v[222:225], v[14:17]
	v_mfma_f32_16x16x32_bf16 v[10:13], v[198:201], v[222:225], v[10:13]
	v_mfma_f32_16x16x32_bf16 v[6:9], v[190:193], v[230:233], v[6:9]
	v_mfma_f32_16x16x32_bf16 v[2:5], v[198:201], v[230:233], v[2:5]
	v_mfma_f32_16x16x32_bf16 v[30:33], v[194:197], v[210:213], v[30:33]
	v_mfma_f32_16x16x32_bf16 v[26:29], v[202:205], v[210:213], v[26:29]
	v_mfma_f32_16x16x32_bf16 v[22:25], v[194:197], v[218:221], v[22:25]
	v_mfma_f32_16x16x32_bf16 v[18:21], v[202:205], v[218:221], v[18:21]
	v_mfma_f32_16x16x32_bf16 v[14:17], v[194:197], v[226:229], v[14:17]
	v_mfma_f32_16x16x32_bf16 v[10:13], v[202:205], v[226:229], v[10:13]
	v_mfma_f32_16x16x32_bf16 v[6:9], v[194:197], v[234:237], v[6:9]
	v_mfma_f32_16x16x32_bf16 v[2:5], v[202:205], v[234:237], v[2:5]
	s_setprio 0
	s_barrier
	s_add_i32 s70, s70, 2
	s_add_u32 s68, s68, 0x100
	s_addc_u32 s69, s69, 0
	s_add_u32 s46, s46, 0x10000
	s_addc_u32 s47, s47, 0
	s_add_u32 s82, s82, 0x10000
	s_addc_u32 s83, s83, 0
	s_mov_b64 s[48:49], 0x10000
	s_cmp_gt_u32 s70, 13
	s_cbranch_scc0 .LBB0_402
	s_and_b64 vcc, exec, s[36:37]
	s_cbranch_vccz .LBB0_405
	s_barrier

; #define PG8_LAS __attribute__((address_space(3)))
; #define PG8_STAGE(bufoff, gbase, voff) do { _Pragma("unroll") for (int _i = 0; _i < 2; ++_i) \
;         __builtin_amdgcn_global_load_lds((const unsigned*)((const char*)(gbase) + (voff)[_i]), (PG8_LAS unsigned*)(lds + (bufoff) + ldsw + _i * 8192), 16, 0, 0); } while (0)
; #define PG8_WAIT_V(n) asm volatile("s_waitcnt vmcnt(" #n ")" ::: "memory")
; #define PG8_BAR __builtin_amdgcn_s_barrier()
; #define S xcd_barrier(bar);
; template <class Epi, bool ALIGN_EPI, bool ABLK = false>
; __device__ __forceinline__ void gemm_phase(PG8_LAS unsigned char* lds, const Gemm g, const StaticOrder& S, const Epi& E) {
;     ...
;                 for (int n = 0; n < 2; ++n) acc[a][b][m][n] = (f32x4){0.f, 0.f, 0.f, 0.f};
;     bf16x8 At[4][2], B0[2][2], B1[2][2];
;     const char* cA = PG8_ABASE(cur); const char* cB = PG8_BBASE(cur);
;     constexpr int RS_MAXT = 12;
;     PG8_LAS float* RS = (PG8_LAS float*)(lds + EX_OFF);
;     f32x4 rq[RS_MAXT][2];
;     if constexpr (Epi::RSTD_LDS) {
; #pragma unroll
;         for (int i = 0; i < RS_MAXT; ++i) { Unit t; if (S.next(i, t)) { const float* p = E.ssqp + (size_t)(t.pm * BM + wid * 32 + (lane & 31)) * 16 + (lane >> 5) * 8; rq[i][0] = *(const f32x4*)p; rq[i][1] = *(const f32x4*)(p + 4); } }
;     }
;     PG8_STAGE(PG8_SB(0, 0), cB, voffB); PG8_STAGE(PG8_SB(0, 1), cB + hstepB, voffB); PG8_STAGE(PG8_SA(0, 0), cA, voffA); PG8_STAGE(PG8_SA(0, 1), cA + hstepA, voffA);
;     if constexpr (Epi::RSTD_LDS) {
;         const int prow = wid * 32 + (lane & 31), slot = (((prow >> 6) & 1) * 16 + (prow & 15)) * 8 + (prow >> 7) * 4 + ((prow >> 4) & 3);
; #pragma unroll
;         for (int i = 0; i < RS_MAXT; ++i) { Unit t; if (S.next(i, t)) {
;             float sm = ((rq[i][0].x + rq[i][0].y) + (rq[i][0].z + rq[i][0].w)) + ((rq[i][1].x + rq[i][1].y) + (rq[i][1].z + rq[i][1].w));
;             sm += __shfl_xor(sm, 32);
;             if (lane < 32) RS[i * 256 + slot] = __builtin_amdgcn_rsqf(sm * (1.0f / D) + EPS); } }
;     }
;     if (wr == 1) PG8_BAR;
;     PG8_WAIT_V(2); PG8_BAR;
;     PG8_STAGE(PG8_SB(1, 0), cB + kstepB, voffB); PG8_STAGE(PG8_SA(1, 0), cA + kstepA, voffA); PG8_STAGE(PG8_SB(1, 1), cB + hstepB + kstepB, voffB);
;     PG8_WAIT_V(6); PG8_BAR;
.LBB0_812:
	s_add_u32 s82, s96, 0x1bf40000
	s_addc_u32 s83, s97, 0
	v_and_b32_e32 v196, 15, v0
	v_and_b32_e32 v9, 48, v0
	v_lshlrev_b32_e32 v11, 2, v0
	s_and_b32 s5, s0, 0x60
	v_lshlrev_b32_e32 v12, 6, v0
	s_movk_i32 s0, 0x3c0
	s_mov_b64 s[46:47], 0x80
	s_lshl_b32 s1, s4, 13
	v_lshl_or_b32 v10, v196, 6, v9
	v_and_b32_e32 v11, 32, v11
	v_and_or_b32 v9, v12, s0, v9
	s_lshl_b32 s0, s5, 7
	s_add_i32 m0, s35, 0x18000
	v_lshl_add_u64 v[2:3], v[2:3], 0, s[46:47]
	s_lshl_b32 s17, s4, 6
	v_bitop3_b32 v10, v10, s1, v11 bitop3:0xde
	v_bitop3_b32 v197, s0, v9, v11 bitop3:0xf6
	s_waitcnt vmcnt(2)
	s_barrier
	global_load_lds_dwordx4 v[2:3], off
	v_lshl_add_u64 v[2:3], v[4:5], 0, s[46:47]
	s_add_i32 m0, s35, 0x1a000
	s_mov_b64 s[48:49], 0x8000
	s_add_i32 s0, s35, 0x8000
	s_add_i32 s1, s35, 0xa000
	global_load_lds_dwordx4 v[2:3], off
	v_lshl_add_u64 v[2:3], v[98:99], 0, s[48:49]
	s_mov_b32 m0, s0
	s_mov_b64 s[50:51], 0xa000
	s_add_u32 s8, s36, 0x40080
	global_load_lds_dwordx4 v[2:3], off
	v_lshl_add_u64 v[2:3], v[98:99], 0, s[50:51]
	s_mov_b32 m0, s1
	s_addc_u32 s9, s37, 0
	global_load_lds_dwordx4 v[2:3], off
	s_add_i32 m0, s35, 0x1c000
	v_lshl_add_u64 v[2:3], s[8:9], 0, v[156:157]
	global_load_lds_dwordx4 v[2:3], off
	v_lshl_add_u64 v[2:3], s[8:9], 0, v[158:159]
	s_add_i32 m0, s35, 0x1e000
	v_lshrrev_b32_e32 v8, 1, v100
	global_load_lds_dwordx4 v[2:3], off
	v_and_or_b32 v160, v8, 24, s5
	v_mov_b32_e32 v163, 0
	v_lshlrev_b32_e32 v162, 2, v160
	v_and_b32_e32 v2, 48, v100
	v_mov_b32_e32 v3, v163
	v_lshl_add_u64 v[166:167], s[6:7], 0, v[2:3]
	v_lshl_add_u64 v[2:3], s[94:95], 0, v[162:163]
	s_mov_b64 s[6:7], 0x8a00000
	v_lshl_add_u64 v[168:169], v[2:3], 0, s[6:7]
	s_mov_b64 s[6:7], 0x8a80000
	v_lshl_add_u64 v[170:171], v[2:3], 0, s[6:7]
	s_mov_b64 s[6:7], 0x8500000
	s_cmpk_lt_u32 s12, 0x100
	v_lshl_add_u64 v[172:173], v[2:3], 0, s[6:7]
	s_mov_b64 s[6:7], 0x8580000
	s_cselect_b64 s[52:53], -1, 0
	s_lshl_b32 s4, s4, 9
	v_lshl_add_u64 v[174:175], v[2:3], 0, s[6:7]
	v_xor_b32_e32 v2, 16, v6
	s_waitcnt vmcnt(6)
	s_add_i32 s4, s4, 0
	v_cmp_lt_i32_e32 vcc, v2, v7
	s_add_i32 s4, s4, 0x20000
	s_mov_b32 s85, 0
	v_cndmask_b32_e32 v2, v6, v2, vcc
	v_or_b32_e32 v198, 0xfffe0060, v196
	v_lshl_add_u32 v199, v196, 5, s4
	v_cmp_gt_u32_e64 s[4:5], 16, v160
	v_or_b32_e32 v200, 16, v196
	v_or_b32_e32 v201, 32, v196
	v_or_b32_e32 v202, 48, v196
	v_or_b32_e32 v203, 0xfffe0070, v196
	v_lshl_add_u64 v[164:165], s[80:81], 0, v[162:163]
	v_lshlrev_b32_e32 v204, 2, v2
	v_mov_b64_e32 v[176:177], 0x8ff
	s_add_i32 s42, 0, 0x10000
	s_add_i32 s43, 0, 0x14000
	v_add_u32_e32 v205, 0, v10
	v_mov_b32_e32 v206, 0x358637bd
	v_mov_b32_e32 v207, 0x3db504f3
	v_mov_b32_e32 v208, 0xfcf
	v_mov_b32_e32 v209, 0xfdf
	v_mov_b32_e32 v210, 0xfef
	v_mov_b32_e32 v211, 0xfff
	s_mov_b32 s44, 0
	v_mov_b32_e32 v2, v163
	v_mov_b32_e32 v3, v163
	v_mov_b32_e32 v4, v163
	v_mov_b32_e32 v5, v163
	v_mov_b32_e32 v6, v163
	v_mov_b32_e32 v7, v163
	v_mov_b32_e32 v8, v163
	v_mov_b32_e32 v9, v163
	v_mov_b32_e32 v10, v163
	v_mov_b32_e32 v11, v163
	v_mov_b32_e32 v12, v163
	v_mov_b32_e32 v13, v163
	v_mov_b32_e32 v14, v163
	v_mov_b32_e32 v15, v163
	v_mov_b32_e32 v16, v163
	v_mov_b32_e32 v17, v163
	v_mov_b32_e32 v18, v163
	v_mov_b32_e32 v19, v163
	v_mov_b32_e32 v20, v163
	v_mov_b32_e32 v21, v163
	v_mov_b32_e32 v22, v163
	v_mov_b32_e32 v23, v163
	v_mov_b32_e32 v24, v163
	v_mov_b32_e32 v25, v163
	v_mov_b32_e32 v26, v163
	v_mov_b32_e32 v27, v163
	v_mov_b32_e32 v28, v163
	v_mov_b32_e32 v29, v163
	v_mov_b32_e32 v30, v163
	v_mov_b32_e32 v31, v163
	v_mov_b32_e32 v32, v163
	v_mov_b32_e32 v33, v163
	v_mov_b32_e32 v34, v163
	v_mov_b32_e32 v35, v163
	v_mov_b32_e32 v36, v163
	v_mov_b32_e32 v37, v163
	v_mov_b32_e32 v38, v163
	v_mov_b32_e32 v39, v163
	v_mov_b32_e32 v40, v163
	v_mov_b32_e32 v41, v163
	v_mov_b32_e32 v42, v163
	v_mov_b32_e32 v43, v163
	v_mov_b32_e32 v44, v163
	v_mov_b32_e32 v45, v163
	v_mov_b32_e32 v46, v163
	v_mov_b32_e32 v47, v163
	v_mov_b32_e32 v48, v163
	v_mov_b32_e32 v49, v163
	v_mov_b32_e32 v50, v163
	v_mov_b32_e32 v51, v163
	v_mov_b32_e32 v52, v163
	v_mov_b32_e32 v53, v163
	v_mov_b32_e32 v54, v163
	v_mov_b32_e32 v55, v163
	v_mov_b32_e32 v56, v163
	v_mov_b32_e32 v57, v163
	v_mov_b32_e32 v58, v163
	v_mov_b32_e32 v59, v163
	v_mov_b32_e32 v60, v163
	v_mov_b32_e32 v61, v163
	v_mov_b32_e32 v62, v163
	v_mov_b32_e32 v63, v163
	v_mov_b32_e32 v64, v163
	v_mov_b32_e32 v65, v163
	v_mov_b32_e32 v66, v163
	v_mov_b32_e32 v67, v163
	v_mov_b32_e32 v68, v163
	v_mov_b32_e32 v69, v163
	v_mov_b32_e32 v70, v163
	v_mov_b32_e32 v71, v163
	v_mov_b32_e32 v72, v163
	v_mov_b32_e32 v73, v163
	v_mov_b32_e32 v74, v163
	v_mov_b32_e32 v75, v163
	v_mov_b32_e32 v76, v163
	v_mov_b32_e32 v77, v163
	v_mov_b32_e32 v78, v163
	v_mov_b32_e32 v79, v163
	v_mov_b32_e32 v80, v163
	v_mov_b32_e32 v81, v163
	v_mov_b32_e32 v82, v163
	v_mov_b32_e32 v83, v163
	v_mov_b32_e32 v84, v163
	v_mov_b32_e32 v85, v163
	v_mov_b32_e32 v86, v163
	v_mov_b32_e32 v87, v163
	v_mov_b32_e32 v88, v163
	v_mov_b32_e32 v89, v163
	v_mov_b32_e32 v90, v163
	v_mov_b32_e32 v91, v163
	v_mov_b32_e32 v92, v163
	v_mov_b32_e32 v93, v163
	v_mov_b32_e32 v94, v163
	v_mov_b32_e32 v95, v163
	v_mov_b32_e32 v96, v163
	v_mov_b32_e32 v97, v163
	v_mov_b32_e32 v98, v163
	v_mov_b32_e32 v99, v163
	v_mov_b32_e32 v100, v163
	v_mov_b32_e32 v101, v163
	v_mov_b32_e32 v102, v163
	v_mov_b32_e32 v103, v163
	v_mov_b32_e32 v104, v163
	v_mov_b32_e32 v105, v163
	v_mov_b32_e32 v106, v163
	v_mov_b32_e32 v107, v163
	v_mov_b32_e32 v108, v163
	v_mov_b32_e32 v109, v163
	v_mov_b32_e32 v110, v163
	v_mov_b32_e32 v111, v163
	v_mov_b32_e32 v112, v163
	v_mov_b32_e32 v113, v163
	v_mov_b32_e32 v114, v163
	v_mov_b32_e32 v115, v163
	v_mov_b32_e32 v116, v163
	v_mov_b32_e32 v117, v163
	v_mov_b32_e32 v118, v163
	v_mov_b32_e32 v119, v163
	v_mov_b32_e32 v120, v163
	v_mov_b32_e32 v121, v163
	v_mov_b32_e32 v122, v163
	v_mov_b32_e32 v123, v163
	v_mov_b32_e32 v124, v163
	v_mov_b32_e32 v125, v163
	v_mov_b32_e32 v126, v163
	v_mov_b32_e32 v127, v163
	v_mov_b32_e32 v128, v163
	v_mov_b32_e32 v129, v163
	s_barrier
	s_mov_b32 s88, 0
	s_branch .LBB0_815

; #define PG8_STAGE(bufoff, gbase, voff) do { _Pragma("unroll") for (int _i = 0; _i < 2; ++_i) \
;         __builtin_amdgcn_global_load_lds((const unsigned*)((const char*)(gbase) + (voff)[_i]), (PG8_LAS unsigned*)(lds + (bufoff) + ldsw + _i * 8192), 16, 0, 0); } while (0)
; #define PG8_LDA(dst, b, h) do { _Pragma("unroll") for (int m = 0; m < 4; ++m) _Pragma("unroll") for (int k = 0; k < 2; ++k) dst[m][k] = *(const PG8_LAS bf16x8*)(lds + PG8_SA(b, h) + aoff + m * 2048 + k * 1024); } while (0)
; #define PG8_LDB(dst, b, h) do { _Pragma("unroll") for (int n = 0; n < 2; ++n) _Pragma("unroll") for (int k = 0; k < 2; ++k) dst[n][k] = *(const PG8_LAS bf16x8*)(lds + PG8_SB(b, h) + boff + n * 2048 + k * 1024); } while (0)
; #define PG8_MMA(ai, bj, At, Bt) do { __builtin_amdgcn_s_setprio(1); _Pragma("unroll") for (int m = 0; m < 4; ++m) _Pragma("unroll") for (int n = 0; n < 2; ++n) _Pragma("unroll") for (int k = 0; k < 2; ++k) \
;         acc[ai][bj][m][n] = __builtin_amdgcn_mfma_f32_16x16x32_bf16(Bt[n][k], At[m][k], acc[ai][bj][m][n], 0, 0, 0); __builtin_amdgcn_s_setprio(0); } while (0)
; #define PG8_WAIT_V(n) asm volatile("s_waitcnt vmcnt(" #n ")" ::: "memory")
; #define PG8_WAIT_L(n) asm volatile("s_waitcnt lgkmcnt(" #n ")" ::: "memory")
; #define PG8_BAR __builtin_amdgcn_s_barrier()
; #define PG8_SCHED __builtin_amdgcn_sched_barrier(0)
; template <class Epi, bool ALIGN_EPI, bool ABLK = false>
; __device__ __forceinline__ void gemm_phase(PG8_LAS unsigned char* lds, const Gemm g, const StaticOrder& S, const Epi& E) {
;     ...
;             PG8_LDB(B0, 0, 0); PG8_LDB(B1, 0, 1); PG8_SCHED; PG8_LDA(At, 0, 0); PG8_STAGE(PG8_SA(1, 1), a1 + hstepA, voffA);
;             PG8_WAIT_V(8); PG8_WAIT_L(0); PG8_BAR; PG8_MMA(0, 0, At, B0); PG8_MMA(0, 1, At, B1); PG8_BAR; PG8_SCHED;
.LBB0_818:
	ds_read_b128 v[132:135], v153
	ds_read_b128 v[136:139], v153 offset:1024
	ds_read_b128 v[140:143], v153 offset:2048
	ds_read_b128 v[144:147], v153 offset:3072
	ds_read_b128 v[148:151], v153 offset:16384
	ds_read_b128 v[178:181], v153 offset:17408
	ds_read_b128 v[182:185], v153 offset:18432
	ds_read_b128 v[212:215], v153 offset:19456
	s_add_u32 s12, s38, s10
	s_addc_u32 s13, s39, s11
	s_sub_u32 s98, s12, 0x10000
	s_subb_u32 s99, s13, 0
	s_cmp_eq_u32 s65, 12
	s_cselect_b32 s101, s33, s13
	s_cselect_b32 s100, s57, s12
	s_cselect_b32 s13, s55, s64
	s_cselect_b32 s12, s62, s63
	s_mov_b64 s[68:69], 0xc000
	s_add_i32 m0, s35, 0xc000
	s_mov_b64 s[68:69], 0xe000
	ds_read_b128 v[216:219], v205
	ds_read_b128 v[220:223], v205 offset:1024
	ds_read_b128 v[224:227], v205 offset:2048
	ds_read_b128 v[228:231], v205 offset:3072
	ds_read_b128 v[232:235], v205 offset:4096
	ds_read_b128 v[236:239], v205 offset:5120
	ds_read_b128 v[240:243], v205 offset:6144
	ds_read_b128 v[244:247], v205 offset:7168
	global_load_lds_dwordx4 v253, s[98:99]
	s_add_i32 m0, s35, 0xe000
	s_nop 0
	global_load_lds_dwordx4 v152, s[98:99]
	s_cmp_lg_u32 s65, -2
	s_cbranch_scc1 .Lrw_p3_0_n
	s_cmp_eq_u32 s88, 0
	s_cbranch_scc1 .Lrw_p3_0_n
	s_waitcnt vmcnt(24)
	s_branch .Lrw_p3_0_d

; #define PG8_STAGE(bufoff, gbase, voff) do { _Pragma("unroll") for (int _i = 0; _i < 2; ++_i) \
;         __builtin_amdgcn_global_load_lds((const unsigned*)((const char*)(gbase) + (voff)[_i]), (PG8_LAS unsigned*)(lds + (bufoff) + ldsw + _i * 8192), 16, 0, 0); } while (0)
; #define PG8_LDA(dst, b, h) do { _Pragma("unroll") for (int m = 0; m < 4; ++m) _Pragma("unroll") for (int k = 0; k < 2; ++k) dst[m][k] = *(const PG8_LAS bf16x8*)(lds + PG8_SA(b, h) + aoff + m * 2048 + k * 1024); } while (0)
; #define PG8_MMA(ai, bj, At, Bt) do { __builtin_amdgcn_s_setprio(1); _Pragma("unroll") for (int m = 0; m < 4; ++m) _Pragma("unroll") for (int n = 0; n < 2; ++n) _Pragma("unroll") for (int k = 0; k < 2; ++k) \
;         acc[ai][bj][m][n] = __builtin_amdgcn_mfma_f32_16x16x32_bf16(Bt[n][k], At[m][k], acc[ai][bj][m][n], 0, 0, 0); __builtin_amdgcn_s_setprio(0); } while (0)
; #define PG8_WAIT_V(n) asm volatile("s_waitcnt vmcnt(" #n ")" ::: "memory")
; #define PG8_WAIT_L(n) asm volatile("s_waitcnt lgkmcnt(" #n ")" ::: "memory")
; #define PG8_BAR __builtin_amdgcn_s_barrier()
; #define PG8_SCHED __builtin_amdgcn_sched_barrier(0)
; template <class Epi, bool ALIGN_EPI, bool ABLK = false>
; __device__ __forceinline__ void gemm_phase(PG8_LAS unsigned char* lds, const Gemm g, const StaticOrder& S, const Epi& E) {
;     ...
;             PG8_WAIT_V(8); PG8_WAIT_L(0); PG8_BAR; PG8_MMA(0, 0, At, B0); PG8_MMA(0, 1, At, B1); PG8_BAR; PG8_SCHED;
;             PG8_LDA(At, 0, 1); PG8_STAGE(PG8_SB(0, 0), b2, voffB); PG8_STAGE(PG8_SB(0, 1), b2 + hstepB, voffB); PG8_STAGE(PG8_SA(0, 0), a2, voffA);
;             PG8_WAIT_V(8); PG8_WAIT_L(0); PG8_BAR; PG8_MMA(1, 0, At, B0); PG8_MMA(1, 1, At, B1); PG8_BAR; PG8_SCHED;
.Lrw_p3_0_d:
	s_waitcnt lgkmcnt(0)
	s_barrier
	s_setprio 1
	s_waitcnt lgkmcnt(0)
	v_mfma_f32_16x16x32_bf16 v[126:129], v[132:135], v[216:219], v[126:129]
	v_mfma_f32_16x16x32_bf16 v[122:125], v[140:143], v[216:219], v[122:125]
	v_mfma_f32_16x16x32_bf16 v[118:121], v[132:135], v[224:227], v[118:121]
	v_mfma_f32_16x16x32_bf16 v[114:117], v[140:143], v[224:227], v[114:117]
	v_mfma_f32_16x16x32_bf16 v[110:113], v[132:135], v[232:235], v[110:113]
	v_mfma_f32_16x16x32_bf16 v[106:109], v[140:143], v[232:235], v[106:109]
	v_mfma_f32_16x16x32_bf16 v[102:105], v[132:135], v[240:243], v[102:105]
	v_mfma_f32_16x16x32_bf16 v[98:101], v[140:143], v[240:243], v[98:101]
	v_mfma_f32_16x16x32_bf16 v[126:129], v[136:139], v[220:223], v[126:129]
	v_mfma_f32_16x16x32_bf16 v[122:125], v[144:147], v[220:223], v[122:125]
	v_mfma_f32_16x16x32_bf16 v[118:121], v[136:139], v[228:231], v[118:121]
	v_mfma_f32_16x16x32_bf16 v[114:117], v[144:147], v[228:231], v[114:117]
	v_mfma_f32_16x16x32_bf16 v[110:113], v[136:139], v[236:239], v[110:113]
	v_mfma_f32_16x16x32_bf16 v[106:109], v[144:147], v[236:239], v[106:109]
	v_mfma_f32_16x16x32_bf16 v[102:105], v[136:139], v[244:247], v[102:105]
	v_mfma_f32_16x16x32_bf16 v[98:101], v[144:147], v[244:247], v[98:101]
	s_setprio 0
	s_setprio 1
	v_mfma_f32_16x16x32_bf16 v[94:97], v[148:151], v[216:219], v[94:97]
	v_mfma_f32_16x16x32_bf16 v[90:93], v[182:185], v[216:219], v[90:93]
	v_mfma_f32_16x16x32_bf16 v[86:89], v[148:151], v[224:227], v[86:89]
	v_mfma_f32_16x16x32_bf16 v[82:85], v[182:185], v[224:227], v[82:85]
	v_mfma_f32_16x16x32_bf16 v[78:81], v[148:151], v[232:235], v[78:81]
	v_mfma_f32_16x16x32_bf16 v[74:77], v[182:185], v[232:235], v[74:77]
	v_mfma_f32_16x16x32_bf16 v[70:73], v[148:151], v[240:243], v[70:73]
	v_mfma_f32_16x16x32_bf16 v[66:69], v[182:185], v[240:243], v[66:69]
	v_mfma_f32_16x16x32_bf16 v[94:97], v[178:181], v[220:223], v[94:97]
	v_mfma_f32_16x16x32_bf16 v[90:93], v[212:215], v[220:223], v[90:93]
	v_mfma_f32_16x16x32_bf16 v[86:89], v[178:181], v[228:231], v[86:89]
	v_mfma_f32_16x16x32_bf16 v[82:85], v[212:215], v[228:231], v[82:85]
	v_mfma_f32_16x16x32_bf16 v[78:81], v[178:181], v[236:239], v[78:81]
	v_mfma_f32_16x16x32_bf16 v[74:77], v[212:215], v[236:239], v[74:77]
	v_mfma_f32_16x16x32_bf16 v[70:73], v[178:181], v[244:247], v[70:73]
	v_mfma_f32_16x16x32_bf16 v[66:69], v[212:215], v[244:247], v[66:69]
	s_setprio 0
	s_barrier
	s_add_i32 s68, s42, s31
	s_mov_b32 m0, s68
	ds_read_b128 v[216:219], v205 offset:16384
	ds_read_b128 v[220:223], v205 offset:17408
	ds_read_b128 v[224:227], v205 offset:18432
	ds_read_b128 v[228:231], v205 offset:19456
	ds_read_b128 v[232:235], v205 offset:20480
	ds_read_b128 v[236:239], v205 offset:21504
	ds_read_b128 v[240:243], v205 offset:22528
	ds_read_b128 v[244:247], v205 offset:23552
	global_load_lds_dwordx4 v156, s[12:13]
	s_add_i32 m0, s68, 0x2000
	s_add_u32 s68, s12, 0x40000
	s_addc_u32 s69, s13, 0
	s_add_i32 s70, s43, s31
	global_load_lds_dwordx4 v158, s[12:13]
	s_mov_b32 m0, s70
	s_nop 0
	global_load_lds_dwordx4 v156, s[68:69]
	s_add_i32 m0, s70, 0x2000
	s_nop 0
	global_load_lds_dwordx4 v158, s[68:69]
	s_mov_b32 m0, s35
	s_mov_b64 s[66:67], 0x2000
	global_load_lds_dwordx4 v154, s[100:101]
	s_mov_b32 m0, s18
	s_nop 0
	global_load_lds_dwordx4 v248, s[100:101]
	s_cmp_lg_u32 s65, -2
	s_cbranch_scc1 .Lrw_p3_1_n
	s_cmp_eq_u32 s88, 0
	s_cbranch_scc1 .Lrw_p3_1_n
	s_waitcnt vmcnt(24)
	s_branch .Lrw_p3_1_d

; #define PG8_STAGE(bufoff, gbase, voff) do { _Pragma("unroll") for (int _i = 0; _i < 2; ++_i) \
;         __builtin_amdgcn_global_load_lds((const unsigned*)((const char*)(gbase) + (voff)[_i]), (PG8_LAS unsigned*)(lds + (bufoff) + ldsw + _i * 8192), 16, 0, 0); } while (0)
; #define PG8_LDA(dst, b, h) do { _Pragma("unroll") for (int m = 0; m < 4; ++m) _Pragma("unroll") for (int k = 0; k < 2; ++k) dst[m][k] = *(const PG8_LAS bf16x8*)(lds + PG8_SA(b, h) + aoff + m * 2048 + k * 1024); } while (0)
; #define PG8_LDB(dst, b, h) do { _Pragma("unroll") for (int n = 0; n < 2; ++n) _Pragma("unroll") for (int k = 0; k < 2; ++k) dst[n][k] = *(const PG8_LAS bf16x8*)(lds + PG8_SB(b, h) + boff + n * 2048 + k * 1024); } while (0)
; #define PG8_MMA(ai, bj, At, Bt) do { __builtin_amdgcn_s_setprio(1); _Pragma("unroll") for (int m = 0; m < 4; ++m) _Pragma("unroll") for (int n = 0; n < 2; ++n) _Pragma("unroll") for (int k = 0; k < 2; ++k) \
;         acc[ai][bj][m][n] = __builtin_amdgcn_mfma_f32_16x16x32_bf16(Bt[n][k], At[m][k], acc[ai][bj][m][n], 0, 0, 0); __builtin_amdgcn_s_setprio(0); } while (0)
; #define PG8_WAIT_V(n) asm volatile("s_waitcnt vmcnt(" #n ")" ::: "memory")
; #define PG8_WAIT_L(n) asm volatile("s_waitcnt lgkmcnt(" #n ")" ::: "memory")
; #define PG8_BAR __builtin_amdgcn_s_barrier()
; #define PG8_SCHED __builtin_amdgcn_sched_barrier(0)
; template <class Epi, bool ALIGN_EPI, bool ABLK = false>
; __device__ __forceinline__ void gemm_phase(PG8_LAS unsigned char* lds, const Gemm g, const StaticOrder& S, const Epi& E) {
;     ...
;             PG8_WAIT_V(8); PG8_WAIT_L(0); PG8_BAR; PG8_MMA(1, 0, At, B0); PG8_MMA(1, 1, At, B1); PG8_BAR; PG8_SCHED;
;             PG8_LDB(B0, 1, 0); PG8_LDB(B1, 1, 1); PG8_SCHED; PG8_LDA(At, 1, 0); PG8_STAGE(PG8_SA(0, 1), a2 + hstepA, voffA);
;             PG8_WAIT_V(8); PG8_WAIT_L(0); PG8_BAR; PG8_MMA(0, 0, At, B0); PG8_MMA(0, 1, At, B1); PG8_BAR; PG8_SCHED;
.Lrw_p3_1_d:
	s_waitcnt lgkmcnt(0)
	s_barrier
	s_setprio 1
	s_waitcnt lgkmcnt(0)
	v_mfma_f32_16x16x32_bf16 v[62:65], v[132:135], v[216:219], v[62:65]
	v_mfma_f32_16x16x32_bf16 v[58:61], v[140:143], v[216:219], v[58:61]
	v_mfma_f32_16x16x32_bf16 v[54:57], v[132:135], v[224:227], v[54:57]
	v_mfma_f32_16x16x32_bf16 v[50:53], v[140:143], v[224:227], v[50:53]
	v_mfma_f32_16x16x32_bf16 v[46:49], v[132:135], v[232:235], v[46:49]
	v_mfma_f32_16x16x32_bf16 v[42:45], v[140:143], v[232:235], v[42:45]
	v_mfma_f32_16x16x32_bf16 v[38:41], v[132:135], v[240:243], v[38:41]
	v_mfma_f32_16x16x32_bf16 v[34:37], v[140:143], v[240:243], v[34:37]
	v_mfma_f32_16x16x32_bf16 v[62:65], v[136:139], v[220:223], v[62:65]
	v_mfma_f32_16x16x32_bf16 v[58:61], v[144:147], v[220:223], v[58:61]
	v_mfma_f32_16x16x32_bf16 v[54:57], v[136:139], v[228:231], v[54:57]
	v_mfma_f32_16x16x32_bf16 v[50:53], v[144:147], v[228:231], v[50:53]
	v_mfma_f32_16x16x32_bf16 v[46:49], v[136:139], v[236:239], v[46:49]
	v_mfma_f32_16x16x32_bf16 v[42:45], v[144:147], v[236:239], v[42:45]
	v_mfma_f32_16x16x32_bf16 v[38:41], v[136:139], v[244:247], v[38:41]
	v_mfma_f32_16x16x32_bf16 v[34:37], v[144:147], v[244:247], v[34:37]
	s_setprio 0
	s_setprio 1
	v_mfma_f32_16x16x32_bf16 v[30:33], v[148:151], v[216:219], v[30:33]
	v_mfma_f32_16x16x32_bf16 v[26:29], v[182:185], v[216:219], v[26:29]
	v_mfma_f32_16x16x32_bf16 v[22:25], v[148:151], v[224:227], v[22:25]
	v_mfma_f32_16x16x32_bf16 v[18:21], v[182:185], v[224:227], v[18:21]
	v_mfma_f32_16x16x32_bf16 v[14:17], v[148:151], v[232:235], v[14:17]
	v_mfma_f32_16x16x32_bf16 v[10:13], v[182:185], v[232:235], v[10:13]
	v_mfma_f32_16x16x32_bf16 v[6:9], v[148:151], v[240:243], v[6:9]
	v_mfma_f32_16x16x32_bf16 v[2:5], v[182:185], v[240:243], v[2:5]
	v_mfma_f32_16x16x32_bf16 v[30:33], v[178:181], v[220:223], v[30:33]
	v_mfma_f32_16x16x32_bf16 v[26:29], v[212:215], v[220:223], v[26:29]
	v_mfma_f32_16x16x32_bf16 v[22:25], v[178:181], v[228:231], v[22:25]
	v_mfma_f32_16x16x32_bf16 v[18:21], v[212:215], v[228:231], v[18:21]
	v_mfma_f32_16x16x32_bf16 v[14:17], v[178:181], v[236:239], v[14:17]
	v_mfma_f32_16x16x32_bf16 v[10:13], v[212:215], v[236:239], v[10:13]
	v_mfma_f32_16x16x32_bf16 v[6:9], v[178:181], v[244:247], v[6:9]
	v_mfma_f32_16x16x32_bf16 v[2:5], v[212:215], v[244:247], v[2:5]
	s_setprio 0
	s_barrier
	s_add_i32 s68, 0, 0x18000
	s_add_i32 s69, 0, 0x1c000
	ds_read_b128 v[132:135], v153 offset:32768
	ds_read_b128 v[136:139], v153 offset:33792
	ds_read_b128 v[140:143], v153 offset:34816
	ds_read_b128 v[144:147], v153 offset:35840
	ds_read_b128 v[148:151], v153 offset:49152
	ds_read_b128 v[178:181], v153 offset:50176
	ds_read_b128 v[182:185], v153 offset:51200
	ds_read_b128 v[212:215], v153 offset:52224
	s_mov_b64 s[66:67], 0x4000
	s_mov_b32 m0, s28
	s_mov_b64 s[66:67], 0x6000
	ds_read_b128 v[216:219], v205 offset:32768
	ds_read_b128 v[220:223], v205 offset:33792
	ds_read_b128 v[224:227], v205 offset:34816
	ds_read_b128 v[228:231], v205 offset:35840
	ds_read_b128 v[232:235], v205 offset:36864
	ds_read_b128 v[236:239], v205 offset:37888
	ds_read_b128 v[240:243], v205 offset:38912
	ds_read_b128 v[244:247], v205 offset:39936
	global_load_lds_dwordx4 v249, s[100:101]
	s_mov_b32 m0, s29
	s_nop 0
	global_load_lds_dwordx4 v250, s[100:101]
	s_waitcnt vmcnt(8)
	s_waitcnt lgkmcnt(0)
	s_barrier
	s_setprio 1
	s_waitcnt lgkmcnt(0)
	v_mfma_f32_16x16x32_bf16 v[126:129], v[132:135], v[216:219], v[126:129]
	v_mfma_f32_16x16x32_bf16 v[122:125], v[140:143], v[216:219], v[122:125]
	v_mfma_f32_16x16x32_bf16 v[118:121], v[132:135], v[224:227], v[118:121]
	v_mfma_f32_16x16x32_bf16 v[114:117], v[140:143], v[224:227], v[114:117]
	v_mfma_f32_16x16x32_bf16 v[110:113], v[132:135], v[232:235], v[110:113]
	v_mfma_f32_16x16x32_bf16 v[106:109], v[140:143], v[232:235], v[106:109]
	v_mfma_f32_16x16x32_bf16 v[102:105], v[132:135], v[240:243], v[102:105]
	v_mfma_f32_16x16x32_bf16 v[98:101], v[140:143], v[240:243], v[98:101]
	v_mfma_f32_16x16x32_bf16 v[126:129], v[136:139], v[220:223], v[126:129]
	v_mfma_f32_16x16x32_bf16 v[122:125], v[144:147], v[220:223], v[122:125]
	v_mfma_f32_16x16x32_bf16 v[118:121], v[136:139], v[228:231], v[118:121]
	v_mfma_f32_16x16x32_bf16 v[114:117], v[144:147], v[228:231], v[114:117]
	v_mfma_f32_16x16x32_bf16 v[110:113], v[136:139], v[236:239], v[110:113]
	v_mfma_f32_16x16x32_bf16 v[106:109], v[144:147], v[236:239], v[106:109]
	v_mfma_f32_16x16x32_bf16 v[102:105], v[136:139], v[244:247], v[102:105]
	v_mfma_f32_16x16x32_bf16 v[98:101], v[144:147], v[244:247], v[98:101]
	s_setprio 0
	s_setprio 1
	v_mfma_f32_16x16x32_bf16 v[94:97], v[148:151], v[216:219], v[94:97]
	v_mfma_f32_16x16x32_bf16 v[90:93], v[182:185], v[216:219], v[90:93]
	v_mfma_f32_16x16x32_bf16 v[86:89], v[148:151], v[224:227], v[86:89]
	v_mfma_f32_16x16x32_bf16 v[82:85], v[182:185], v[224:227], v[82:85]
	v_mfma_f32_16x16x32_bf16 v[78:81], v[148:151], v[232:235], v[78:81]
	v_mfma_f32_16x16x32_bf16 v[74:77], v[182:185], v[232:235], v[74:77]
	v_mfma_f32_16x16x32_bf16 v[70:73], v[148:151], v[240:243], v[70:73]
	v_mfma_f32_16x16x32_bf16 v[66:69], v[182:185], v[240:243], v[66:69]
	v_mfma_f32_16x16x32_bf16 v[94:97], v[178:181], v[220:223], v[94:97]
	v_mfma_f32_16x16x32_bf16 v[90:93], v[212:215], v[220:223], v[90:93]
	v_mfma_f32_16x16x32_bf16 v[86:89], v[178:181], v[228:231], v[86:89]
	v_mfma_f32_16x16x32_bf16 v[82:85], v[212:215], v[228:231], v[82:85]
	v_mfma_f32_16x16x32_bf16 v[78:81], v[178:181], v[236:239], v[78:81]
	v_mfma_f32_16x16x32_bf16 v[74:77], v[212:215], v[236:239], v[74:77]
	v_mfma_f32_16x16x32_bf16 v[70:73], v[178:181], v[244:247], v[70:73]
	v_mfma_f32_16x16x32_bf16 v[66:69], v[212:215], v[244:247], v[66:69]
	s_setprio 0
	s_barrier
; #define PG8_STAGE(bufoff, gbase, voff) do { _Pragma("unroll") for (int _i = 0; _i < 2; ++_i) \
;         __builtin_amdgcn_global_load_lds((const unsigned*)((const char*)(gbase) + (voff)[_i]), (PG8_LAS unsigned*)(lds + (bufoff) + ldsw + _i * 8192), 16, 0, 0); } while (0)
; #define PG8_LDA(dst, b, h) do { _Pragma("unroll") for (int m = 0; m < 4; ++m) _Pragma("unroll") for (int k = 0; k < 2; ++k) dst[m][k] = *(const PG8_LAS bf16x8*)(lds + PG8_SA(b, h) + aoff + m * 2048 + k * 1024); } while (0)
; #define PG8_MMA(ai, bj, At, Bt) do { __builtin_amdgcn_s_setprio(1); _Pragma("unroll") for (int m = 0; m < 4; ++m) _Pragma("unroll") for (int n = 0; n < 2; ++n) _Pragma("unroll") for (int k = 0; k < 2; ++k) \
;         acc[ai][bj][m][n] = __builtin_amdgcn_mfma_f32_16x16x32_bf16(Bt[n][k], At[m][k], acc[ai][bj][m][n], 0, 0, 0); __builtin_amdgcn_s_setprio(0); } while (0)
; #define PG8_WAIT_V(n) asm volatile("s_waitcnt vmcnt(" #n ")" ::: "memory")
; #define PG8_WAIT_L(n) asm volatile("s_waitcnt lgkmcnt(" #n ")" ::: "memory")
; #define PG8_BAR __builtin_amdgcn_s_barrier()
; #define PG8_SCHED __builtin_amdgcn_sched_barrier(0)
; template <class Epi, bool ALIGN_EPI, bool ABLK = false>
; __device__ __forceinline__ void gemm_phase(PG8_LAS unsigned char* lds, const Gemm g, const StaticOrder& S, const Epi& E) {
;     ...
;             PG8_LDA(At, 1, 1); PG8_STAGE(PG8_SB(1, 0), b3, voffB); PG8_STAGE(PG8_SB(1, 1), b3 + hstepB, voffB); PG8_STAGE(PG8_SA(1, 0), a3, voffA);
;             PG8_WAIT_V(8); PG8_WAIT_L(0); PG8_BAR; PG8_MMA(1, 0, At, B0); PG8_MMA(1, 1, At, B1); PG8_BAR; PG8_SCHED;
;         }
	s_add_i32 s66, s68, s31
	s_add_u32 s12, s12, s46
	s_addc_u32 s13, s13, s47
	s_mov_b32 m0, s66
	ds_read_b128 v[216:219], v205 offset:49152
	ds_read_b128 v[220:223], v205 offset:50176
	ds_read_b128 v[224:227], v205 offset:51200
	ds_read_b128 v[228:231], v205 offset:52224
	ds_read_b128 v[232:235], v205 offset:53248
	ds_read_b128 v[236:239], v205 offset:54272
	ds_read_b128 v[240:243], v205 offset:55296
	ds_read_b128 v[244:247], v205 offset:56320
	global_load_lds_dwordx4 v156, s[12:13]
	s_add_i32 m0, s66, 0x2000
	s_add_i32 s66, s69, s31
	global_load_lds_dwordx4 v158, s[12:13]
	s_add_u32 s12, s12, 0x40000
	s_addc_u32 s13, s13, 0
	s_mov_b32 m0, s66
	s_nop 0
	global_load_lds_dwordx4 v156, s[12:13]
	s_add_i32 m0, s66, 0x2000
	s_nop 0
	global_load_lds_dwordx4 v158, s[12:13]
	s_mov_b32 m0, s0
	s_nop 0
	global_load_lds_dwordx4 v251, s[100:101]
	s_mov_b32 m0, s1
	s_nop 0
	global_load_lds_dwordx4 v252, s[100:101]
	s_waitcnt vmcnt(8)
	s_waitcnt lgkmcnt(0)
	s_barrier
	s_setprio 1
	s_waitcnt lgkmcnt(0)
	v_mfma_f32_16x16x32_bf16 v[62:65], v[132:135], v[216:219], v[62:65]
	v_mfma_f32_16x16x32_bf16 v[58:61], v[140:143], v[216:219], v[58:61]
	v_mfma_f32_16x16x32_bf16 v[54:57], v[132:135], v[224:227], v[54:57]
	v_mfma_f32_16x16x32_bf16 v[50:53], v[140:143], v[224:227], v[50:53]
	v_mfma_f32_16x16x32_bf16 v[46:49], v[132:135], v[232:235], v[46:49]
	v_mfma_f32_16x16x32_bf16 v[42:45], v[140:143], v[232:235], v[42:45]
	v_mfma_f32_16x16x32_bf16 v[38:41], v[132:135], v[240:243], v[38:41]
	v_mfma_f32_16x16x32_bf16 v[34:37], v[140:143], v[240:243], v[34:37]
	v_mfma_f32_16x16x32_bf16 v[62:65], v[136:139], v[220:223], v[62:65]
	v_mfma_f32_16x16x32_bf16 v[58:61], v[144:147], v[220:223], v[58:61]
	v_mfma_f32_16x16x32_bf16 v[54:57], v[136:139], v[228:231], v[54:57]
	v_mfma_f32_16x16x32_bf16 v[50:53], v[144:147], v[228:231], v[50:53]
	v_mfma_f32_16x16x32_bf16 v[46:49], v[136:139], v[236:239], v[46:49]
	v_mfma_f32_16x16x32_bf16 v[42:45], v[144:147], v[236:239], v[42:45]
	v_mfma_f32_16x16x32_bf16 v[38:41], v[136:139], v[244:247], v[38:41]
	v_mfma_f32_16x16x32_bf16 v[34:37], v[144:147], v[244:247], v[34:37]
	s_setprio 0
	s_setprio 1
	v_mfma_f32_16x16x32_bf16 v[30:33], v[148:151], v[216:219], v[30:33]
	v_mfma_f32_16x16x32_bf16 v[26:29], v[182:185], v[216:219], v[26:29]
	v_mfma_f32_16x16x32_bf16 v[22:25], v[148:151], v[224:227], v[22:25]
	v_mfma_f32_16x16x32_bf16 v[18:21], v[182:185], v[224:227], v[18:21]
	v_mfma_f32_16x16x32_bf16 v[14:17], v[148:151], v[232:235], v[14:17]
	v_mfma_f32_16x16x32_bf16 v[10:13], v[182:185], v[232:235], v[10:13]
	v_mfma_f32_16x16x32_bf16 v[6:9], v[148:151], v[240:243], v[6:9]
	v_mfma_f32_16x16x32_bf16 v[2:5], v[182:185], v[240:243], v[2:5]
	v_mfma_f32_16x16x32_bf16 v[30:33], v[178:181], v[220:223], v[30:33]
	v_mfma_f32_16x16x32_bf16 v[26:29], v[212:215], v[220:223], v[26:29]
	v_mfma_f32_16x16x32_bf16 v[22:25], v[178:181], v[228:231], v[22:25]
	v_mfma_f32_16x16x32_bf16 v[18:21], v[212:215], v[228:231], v[18:21]
	v_mfma_f32_16x16x32_bf16 v[14:17], v[178:181], v[236:239], v[14:17]
	v_mfma_f32_16x16x32_bf16 v[10:13], v[212:215], v[236:239], v[10:13]
	v_mfma_f32_16x16x32_bf16 v[6:9], v[178:181], v[244:247], v[6:9]
	v_mfma_f32_16x16x32_bf16 v[2:5], v[212:215], v[244:247], v[2:5]
	s_setprio 0
	s_barrier
	s_add_i32 s65, s65, 2
	s_add_u32 s63, s63, 0x100
	s_addc_u32 s64, s64, 0
	s_add_u32 s10, s10, 0x10000
	s_addc_u32 s11, s11, 0
	s_mov_b64 s[12:13], 0x10000
	s_cmp_gt_u32 s65, 13
	s_cbranch_scc0 .LBB0_818
	s_and_b64 vcc, exec, s[52:53]
	s_cbranch_vccz .LBB0_821
	s_barrier
; #define PG8_LAS __attribute__((address_space(3)))
; __device__ __forceinline__ void rows_rstd(float (&rs)[2][4], const float* ssqp, int row0, int fq) {
;     f32x4 q[2][4];
; #pragma unroll
;     for (int ai = 0; ai < 2; ++ai)
; #pragma unroll
;         for (int m = 0; m < 4; ++m) q[ai][m] = *(const f32x4*)(ssqp + (size_t)(row0 + ai * 128 + m * 16) * 16 + fq * 4);
; #pragma unroll
;     for (int ai = 0; ai < 2; ++ai)
; #pragma unroll
;         for (int m = 0; m < 4; ++m) { float s = (q[ai][m].x + q[ai][m].y) + (q[ai][m].z + q[ai][m].w); s += __shfl_xor(s, 16); s += __shfl_xor(s, 32); rs[ai][m] = __builtin_amdgcn_rsqf(s * (1.0f / D) + EPS); }
; }
; template <class Epi, bool ALIGN_EPI, bool ABLK = false>
; __device__ __forceinline__ void gemm_phase(PG8_LAS unsigned char* lds, const Gemm g, const StaticOrder& S, const Epi& E) {
;     ...
;         else if constexpr (Epi::RSTD_LDS) {
;             float rsa[2][4];
;             if (ui < RS_MAXT) { const f32x4 r0 = *(const PG8_LAS f32x4*)(RS + ui * 256 + (wr * 16 + fr) * 8), r1 = *(const PG8_LAS f32x4*)(RS + ui * 256 + (wr * 16 + fr) * 8 + 4);
; #pragma unroll
;                 for (int m = 0; m < 4; ++m) { rsa[0][m] = r0[m]; rsa[1][m] = r1[m]; } }
;             else rows_rstd(rsa, E.ssqp, cur.pm * BM + wr * 64 + fr, fq);
.LBB0_821:
	s_mov_b32 s88, 0
	s_cmp_gt_i32 s44, 11
	s_mov_b64 s[10:11], -1
	s_cbranch_scc0 .LBB0_823
	v_or_b32_e32 v130, s17, v196
	v_lshl_add_u32 v134, s30, 8, v130
	v_ashrrev_i32_e32 v135, 31, v134
	v_lshlrev_b64 v[130:131], 6, v[134:135]
	v_lshl_add_u64 v[136:137], v[166:167], 0, v[130:131]
	global_load_dwordx4 v[130:133], v[136:137], off
	v_or_b32_e32 v138, 16, v134
	v_ashrrev_i32_e32 v139, 31, v138
	v_lshlrev_b64 v[138:139], 6, v[138:139]
	v_lshl_add_u64 v[138:139], v[166:167], 0, v[138:139]
	global_load_dwordx4 v[146:149], v[138:139], off
	v_or_b32_e32 v138, 32, v134
	v_ashrrev_i32_e32 v139, 31, v138
	v_lshlrev_b64 v[138:139], 6, v[138:139]
	v_lshl_add_u64 v[138:139], v[166:167], 0, v[138:139]
	global_load_dwordx4 v[150:153], v[138:139], off
	v_or_b32_e32 v134, 48, v134
	v_ashrrev_i32_e32 v135, 31, v134
	v_lshlrev_b64 v[134:135], 6, v[134:135]
	v_lshl_add_u64 v[134:135], v[166:167], 0, v[134:135]
	global_load_dwordx4 v[178:181], v[134:135], off
	s_movk_i32 s10, 0x2000
	v_add_co_u32_e32 v134, vcc, s10, v136
	s_nop 1
	v_addc_co_u32_e32 v135, vcc, 0, v137, vcc
	global_load_dwordx4 v[182:185], v[134:135], off
	global_load_dwordx4 v[212:215], v[134:135], off offset:1024
	global_load_dwordx4 v[142:145], v[134:135], off offset:2048
	global_load_dwordx4 v[138:141], v[134:135], off offset:3072
	s_waitcnt vmcnt(0)
	v_mov_b32_e32 v134, v131
	v_mov_b32_e32 v135, v132
	v_mov_b32_e32 v131, v133
	v_pk_add_f32 v[130:131], v[134:135], v[130:131]
	v_mov_b32_e32 v132, v213
	v_add_f32_e32 v130, v130, v131
	ds_bpermute_b32 v131, v204, v130
	v_mov_b32_e32 v133, v214
	v_mov_b32_e32 v213, v215
	v_pk_add_f32 v[132:133], v[132:133], v[212:213]
	s_waitcnt lgkmcnt(0)
	v_add_f32_e32 v130, v130, v131
	ds_bpermute_b32 v131, v195, v130
	s_waitcnt lgkmcnt(0)
	v_add_f32_e32 v130, v130, v131
	v_fmamk_f32 v130, v130, 0x3a800000, v206
	v_rsq_f32_e32 v134, v130
	v_mov_b32_e32 v130, v147
	v_mov_b32_e32 v131, v148
	v_mov_b32_e32 v147, v149
	v_pk_add_f32 v[130:131], v[130:131], v[146:147]
	s_nop 0
	v_add_f32_e32 v130, v130, v131
	ds_bpermute_b32 v131, v204, v130
	s_waitcnt lgkmcnt(0)
	v_add_f32_e32 v130, v130, v131
	ds_bpermute_b32 v131, v195, v130
	s_waitcnt lgkmcnt(0)
	v_add_f32_e32 v130, v130, v131
	v_fmamk_f32 v130, v130, 0x3a800000, v206
	v_rsq_f32_e32 v135, v130
	v_mov_b32_e32 v130, v151
	v_mov_b32_e32 v131, v152
	v_mov_b32_e32 v151, v153
	v_pk_add_f32 v[130:131], v[130:131], v[150:151]
	s_nop 0
	v_add_f32_e32 v130, v130, v131
	ds_bpermute_b32 v131, v204, v130
	s_waitcnt lgkmcnt(0)
	v_add_f32_e32 v130, v130, v131
	ds_bpermute_b32 v131, v195, v130
	s_waitcnt lgkmcnt(0)
	v_add_f32_e32 v130, v130, v131
	v_fmamk_f32 v130, v130, 0x3a800000, v206
	v_rsq_f32_e32 v136, v130
	v_mov_b32_e32 v130, v179
	v_mov_b32_e32 v131, v180
	v_mov_b32_e32 v179, v181
	v_pk_add_f32 v[130:131], v[130:131], v[178:179]
	s_nop 0
	v_add_f32_e32 v130, v130, v131
	ds_bpermute_b32 v131, v204, v130
	s_waitcnt lgkmcnt(0)
	v_add_f32_e32 v130, v130, v131
	ds_bpermute_b32 v131, v195, v130
	s_waitcnt lgkmcnt(0)
	v_add_f32_e32 v130, v130, v131
	v_fmamk_f32 v130, v130, 0x3a800000, v206
	v_rsq_f32_e32 v137, v130
	v_mov_b32_e32 v130, v183
	v_mov_b32_e32 v131, v184
	v_mov_b32_e32 v183, v185
	v_pk_add_f32 v[130:131], v[130:131], v[182:183]
	s_nop 0
	v_add_f32_e32 v130, v130, v131
	ds_bpermute_b32 v131, v204, v130
	s_waitcnt lgkmcnt(0)
	v_add_f32_e32 v130, v130, v131
	ds_bpermute_b32 v131, v195, v130
	s_waitcnt lgkmcnt(0)
	v_add_f32_e32 v130, v130, v131
	v_add_f32_e32 v131, v132, v133
	ds_bpermute_b32 v132, v204, v131
	v_mov_b32_e32 v133, v144
	v_fmamk_f32 v130, v130, 0x3a800000, v206
	v_rsq_f32_e32 v130, v130
	s_waitcnt lgkmcnt(0)
	v_add_f32_e32 v131, v131, v132
	ds_bpermute_b32 v132, v195, v131
	s_waitcnt lgkmcnt(0)
	v_add_f32_e32 v131, v131, v132
	v_mov_b32_e32 v132, v143
	v_mov_b32_e32 v143, v145
	v_pk_add_f32 v[132:133], v[132:133], v[142:143]
	v_mov_b32_e32 v142, v139
	v_add_f32_e32 v132, v132, v133
	ds_bpermute_b32 v133, v204, v132
	v_mov_b32_e32 v143, v140
	v_mov_b32_e32 v139, v141
	v_pk_add_f32 v[138:139], v[142:143], v[138:139]
	v_fmamk_f32 v131, v131, 0x3a800000, v206
	s_waitcnt lgkmcnt(0)
	v_add_f32_e32 v132, v132, v133
	ds_bpermute_b32 v133, v195, v132
	v_rsq_f32_e32 v131, v131
	s_waitcnt lgkmcnt(0)
	v_add_f32_e32 v132, v132, v133
	v_add_f32_e32 v133, v138, v139
	ds_bpermute_b32 v138, v204, v133
	v_fmamk_f32 v132, v132, 0x3a800000, v206
	v_rsq_f32_e32 v132, v132
	s_waitcnt lgkmcnt(0)
	v_add_f32_e32 v133, v133, v138
	ds_bpermute_b32 v138, v195, v133
	s_waitcnt lgkmcnt(0)
	v_add_f32_e32 v133, v133, v138
	v_fmamk_f32 v133, v133, 0x3a800000, v206
	v_rsq_f32_e32 v133, v133
	s_cbranch_execnz .LBB0_825
	s_branch .LBB0_824

; #define PG8_STAGE(bufoff, gbase, voff) do { _Pragma("unroll") for (int _i = 0; _i < 2; ++_i) \
;         __builtin_amdgcn_global_load_lds((const unsigned*)((const char*)(gbase) + (voff)[_i]), (PG8_LAS unsigned*)(lds + (bufoff) + ldsw + _i * 8192), 16, 0, 0); } while (0)
; #define PG8_LDA(dst, b, h) do { _Pragma("unroll") for (int m = 0; m < 4; ++m) _Pragma("unroll") for (int k = 0; k < 2; ++k) dst[m][k] = *(const PG8_LAS bf16x8*)(lds + PG8_SA(b, h) + aoff + m * 2048 + k * 1024); } while (0)
; #define PG8_LDB(dst, b, h) do { _Pragma("unroll") for (int n = 0; n < 2; ++n) _Pragma("unroll") for (int k = 0; k < 2; ++k) dst[n][k] = *(const PG8_LAS bf16x8*)(lds + PG8_SB(b, h) + boff + n * 2048 + k * 1024); } while (0)
; #define PG8_MMA(ai, bj, At, Bt) do { __builtin_amdgcn_s_setprio(1); _Pragma("unroll") for (int m = 0; m < 4; ++m) _Pragma("unroll") for (int n = 0; n < 2; ++n) _Pragma("unroll") for (int k = 0; k < 2; ++k) \
;         acc[ai][bj][m][n] = __builtin_amdgcn_mfma_f32_16x16x32_bf16(Bt[n][k], At[m][k], acc[ai][bj][m][n], 0, 0, 0); __builtin_amdgcn_s_setprio(0); } while (0)
; #define PG8_WAIT_V(n) asm volatile("s_waitcnt vmcnt(" #n ")" ::: "memory")
; #define PG8_WAIT_L(n) asm volatile("s_waitcnt lgkmcnt(" #n ")" ::: "memory")
; #define PG8_BAR __builtin_amdgcn_s_barrier()
; #define PG8_SCHED __builtin_amdgcn_sched_barrier(0)
; template <class Epi, bool ALIGN_EPI, bool ABLK = false>
; __device__ __forceinline__ void gemm_phase(PG8_LAS unsigned char* lds, const Gemm g, const StaticOrder& S, const Epi& E) {
;     ...
;             PG8_LDB(B0, 0, 0); PG8_LDB(B1, 0, 1); PG8_SCHED; PG8_LDA(At, 0, 0); PG8_STAGE(PG8_SA(1, 1), a1 + hstepA, voffA);
;             PG8_WAIT_V(8); PG8_WAIT_L(0); PG8_BAR; PG8_MMA(0, 0, At, B0); PG8_MMA(0, 1, At, B1); PG8_BAR; PG8_SCHED;
.LBB0_2495:
	ds_read_b128 v[132:135], v251
	ds_read_b128 v[178:181], v251 offset:1024
	ds_read_b128 v[182:185], v251 offset:2048
	ds_read_b128 v[186:189], v251 offset:3072
	ds_read_b128 v[190:193], v251 offset:16384
	ds_read_b128 v[194:197], v251 offset:17408
	ds_read_b128 v[198:201], v251 offset:18432
	ds_read_b128 v[202:205], v251 offset:19456
	s_add_u32 s60, s24, s58
	s_addc_u32 s61, s25, s59
	s_sub_u32 s98, s60, 0x10000
	s_subb_u32 s99, s61, 0
	s_cmp_eq_u32 s83, 12
	s_cselect_b32 s101, s53, s61
	s_cselect_b32 s100, s79, s60
	s_cselect_b32 s61, s51, s82
	s_cselect_b32 s60, s80, s81
	s_add_i32 m0, s66, 0xc000
	ds_read_b128 v[206:209], v176
	ds_read_b128 v[210:213], v176 offset:1024
	ds_read_b128 v[214:217], v176 offset:2048
	ds_read_b128 v[218:221], v176 offset:3072
	ds_read_b128 v[222:225], v176 offset:4096
	ds_read_b128 v[226:229], v176 offset:5120
	ds_read_b128 v[230:233], v176 offset:6144
	ds_read_b128 v[234:237], v176 offset:7168
	global_load_lds_dwordx4 v249, s[98:99]
	s_add_i32 m0, s66, 0xe000
	s_nop 0
	global_load_lds_dwordx4 v250, s[98:99]
	s_cmp_lg_u32 s83, -2
	s_cbranch_scc1 .Lrw_p9_0_n
	s_cmp_eq_u32 s71, 0
	s_cbranch_scc1 .Lrw_p9_0_n
	s_waitcnt vmcnt(16)
	s_branch .Lrw_p9_0_d

; #define PG8_STAGE(bufoff, gbase, voff) do { _Pragma("unroll") for (int _i = 0; _i < 2; ++_i) \
;         __builtin_amdgcn_global_load_lds((const unsigned*)((const char*)(gbase) + (voff)[_i]), (PG8_LAS unsigned*)(lds + (bufoff) + ldsw + _i * 8192), 16, 0, 0); } while (0)
; #define PG8_LDA(dst, b, h) do { _Pragma("unroll") for (int m = 0; m < 4; ++m) _Pragma("unroll") for (int k = 0; k < 2; ++k) dst[m][k] = *(const PG8_LAS bf16x8*)(lds + PG8_SA(b, h) + aoff + m * 2048 + k * 1024); } while (0)
; #define PG8_MMA(ai, bj, At, Bt) do { __builtin_amdgcn_s_setprio(1); _Pragma("unroll") for (int m = 0; m < 4; ++m) _Pragma("unroll") for (int n = 0; n < 2; ++n) _Pragma("unroll") for (int k = 0; k < 2; ++k) \
;         acc[ai][bj][m][n] = __builtin_amdgcn_mfma_f32_16x16x32_bf16(Bt[n][k], At[m][k], acc[ai][bj][m][n], 0, 0, 0); __builtin_amdgcn_s_setprio(0); } while (0)
; #define PG8_WAIT_V(n) asm volatile("s_waitcnt vmcnt(" #n ")" ::: "memory")
; #define PG8_WAIT_L(n) asm volatile("s_waitcnt lgkmcnt(" #n ")" ::: "memory")
; #define PG8_BAR __builtin_amdgcn_s_barrier()
; #define PG8_SCHED __builtin_amdgcn_sched_barrier(0)
; template <class Epi, bool ALIGN_EPI, bool ABLK = false>
; __device__ __forceinline__ void gemm_phase(PG8_LAS unsigned char* lds, const Gemm g, const StaticOrder& S, const Epi& E) {
;     ...
;             PG8_WAIT_V(8); PG8_WAIT_L(0); PG8_BAR; PG8_MMA(0, 0, At, B0); PG8_MMA(0, 1, At, B1); PG8_BAR; PG8_SCHED;
;             PG8_LDA(At, 0, 1); PG8_STAGE(PG8_SB(0, 0), b2, voffB); PG8_STAGE(PG8_SB(0, 1), b2 + hstepB, voffB); PG8_STAGE(PG8_SA(0, 0), a2, voffA);
;             PG8_WAIT_V(8); PG8_WAIT_L(0); PG8_BAR; PG8_MMA(1, 0, At, B0); PG8_MMA(1, 1, At, B1); PG8_BAR; PG8_SCHED;
.Lrw_p9_0_d:
	s_waitcnt lgkmcnt(0)
	s_barrier
	s_setprio 1
	s_waitcnt lgkmcnt(0)
	v_mfma_f32_16x16x32_bf16 v[126:129], v[132:135], v[206:209], v[126:129]
	v_mfma_f32_16x16x32_bf16 v[122:125], v[182:185], v[206:209], v[122:125]
	v_mfma_f32_16x16x32_bf16 v[118:121], v[132:135], v[214:217], v[118:121]
	v_mfma_f32_16x16x32_bf16 v[114:117], v[182:185], v[214:217], v[114:117]
	v_mfma_f32_16x16x32_bf16 v[110:113], v[132:135], v[222:225], v[110:113]
	v_mfma_f32_16x16x32_bf16 v[106:109], v[182:185], v[222:225], v[106:109]
	v_mfma_f32_16x16x32_bf16 v[102:105], v[132:135], v[230:233], v[102:105]
	v_mfma_f32_16x16x32_bf16 v[98:101], v[182:185], v[230:233], v[98:101]
	v_mfma_f32_16x16x32_bf16 v[126:129], v[178:181], v[210:213], v[126:129]
	v_mfma_f32_16x16x32_bf16 v[122:125], v[186:189], v[210:213], v[122:125]
	v_mfma_f32_16x16x32_bf16 v[118:121], v[178:181], v[218:221], v[118:121]
	v_mfma_f32_16x16x32_bf16 v[114:117], v[186:189], v[218:221], v[114:117]
	v_mfma_f32_16x16x32_bf16 v[110:113], v[178:181], v[226:229], v[110:113]
	v_mfma_f32_16x16x32_bf16 v[106:109], v[186:189], v[226:229], v[106:109]
	v_mfma_f32_16x16x32_bf16 v[102:105], v[178:181], v[234:237], v[102:105]
	v_mfma_f32_16x16x32_bf16 v[98:101], v[186:189], v[234:237], v[98:101]
	s_setprio 0
	s_setprio 1
	v_mfma_f32_16x16x32_bf16 v[94:97], v[190:193], v[206:209], v[94:97]
	v_mfma_f32_16x16x32_bf16 v[90:93], v[198:201], v[206:209], v[90:93]
	v_mfma_f32_16x16x32_bf16 v[86:89], v[190:193], v[214:217], v[86:89]
	v_mfma_f32_16x16x32_bf16 v[82:85], v[198:201], v[214:217], v[82:85]
	v_mfma_f32_16x16x32_bf16 v[78:81], v[190:193], v[222:225], v[78:81]
	v_mfma_f32_16x16x32_bf16 v[74:77], v[198:201], v[222:225], v[74:77]
	v_mfma_f32_16x16x32_bf16 v[70:73], v[190:193], v[230:233], v[70:73]
	v_mfma_f32_16x16x32_bf16 v[66:69], v[198:201], v[230:233], v[66:69]
	v_mfma_f32_16x16x32_bf16 v[94:97], v[194:197], v[210:213], v[94:97]
	v_mfma_f32_16x16x32_bf16 v[90:93], v[202:205], v[210:213], v[90:93]
	v_mfma_f32_16x16x32_bf16 v[86:89], v[194:197], v[218:221], v[86:89]
	v_mfma_f32_16x16x32_bf16 v[82:85], v[202:205], v[218:221], v[82:85]
	v_mfma_f32_16x16x32_bf16 v[78:81], v[194:197], v[226:229], v[78:81]
	v_mfma_f32_16x16x32_bf16 v[74:77], v[202:205], v[226:229], v[74:77]
	v_mfma_f32_16x16x32_bf16 v[70:73], v[194:197], v[234:237], v[70:73]
	v_mfma_f32_16x16x32_bf16 v[66:69], v[202:205], v[234:237], v[66:69]
	s_setprio 0
	s_barrier
	s_add_i32 s86, s75, s9
	s_mov_b32 m0, s86
	ds_read_b128 v[206:209], v176 offset:16384
	ds_read_b128 v[210:213], v176 offset:17408
	ds_read_b128 v[214:217], v176 offset:18432
	ds_read_b128 v[218:221], v176 offset:19456
	ds_read_b128 v[222:225], v176 offset:20480
	ds_read_b128 v[226:229], v176 offset:21504
	ds_read_b128 v[230:233], v176 offset:22528
	ds_read_b128 v[234:237], v176 offset:23552
	global_load_lds_dwordx4 v140, s[60:61]
	s_add_i32 m0, s86, 0x2000
	s_add_u32 s86, s60, 0x40000
	s_addc_u32 s87, s61, 0
	s_add_i32 s88, s76, s9
	global_load_lds_dwordx4 v142, s[60:61]
	s_mov_b32 m0, s88
	s_nop 0
	global_load_lds_dwordx4 v140, s[86:87]
	s_add_i32 m0, s88, 0x2000
	s_nop 0
	global_load_lds_dwordx4 v142, s[86:87]
	s_mov_b32 m0, s66
	s_nop 0
	global_load_lds_dwordx4 v138, s[100:101]
	s_mov_b32 m0, s67
	s_nop 0
	global_load_lds_dwordx4 v244, s[100:101]
	s_cmp_lg_u32 s83, -2
	s_cbranch_scc1 .Lrw_p9_1_n
	s_cmp_eq_u32 s71, 0
	s_cbranch_scc1 .Lrw_p9_1_n
	s_waitcnt vmcnt(16)
	s_branch .Lrw_p9_1_d

; #define PG8_STAGE(bufoff, gbase, voff) do { _Pragma("unroll") for (int _i = 0; _i < 2; ++_i) \
;         __builtin_amdgcn_global_load_lds((const unsigned*)((const char*)(gbase) + (voff)[_i]), (PG8_LAS unsigned*)(lds + (bufoff) + ldsw + _i * 8192), 16, 0, 0); } while (0)
; #define PG8_LDA(dst, b, h) do { _Pragma("unroll") for (int m = 0; m < 4; ++m) _Pragma("unroll") for (int k = 0; k < 2; ++k) dst[m][k] = *(const PG8_LAS bf16x8*)(lds + PG8_SA(b, h) + aoff + m * 2048 + k * 1024); } while (0)
; #define PG8_LDB(dst, b, h) do { _Pragma("unroll") for (int n = 0; n < 2; ++n) _Pragma("unroll") for (int k = 0; k < 2; ++k) dst[n][k] = *(const PG8_LAS bf16x8*)(lds + PG8_SB(b, h) + boff + n * 2048 + k * 1024); } while (0)
; #define PG8_MMA(ai, bj, At, Bt) do { __builtin_amdgcn_s_setprio(1); _Pragma("unroll") for (int m = 0; m < 4; ++m) _Pragma("unroll") for (int n = 0; n < 2; ++n) _Pragma("unroll") for (int k = 0; k < 2; ++k) \
;         acc[ai][bj][m][n] = __builtin_amdgcn_mfma_f32_16x16x32_bf16(Bt[n][k], At[m][k], acc[ai][bj][m][n], 0, 0, 0); __builtin_amdgcn_s_setprio(0); } while (0)
; #define PG8_WAIT_V(n) asm volatile("s_waitcnt vmcnt(" #n ")" ::: "memory")
; #define PG8_WAIT_L(n) asm volatile("s_waitcnt lgkmcnt(" #n ")" ::: "memory")
; #define PG8_BAR __builtin_amdgcn_s_barrier()
; #define PG8_SCHED __builtin_amdgcn_sched_barrier(0)
; template <class Epi, bool ALIGN_EPI, bool ABLK = false>
; __device__ __forceinline__ void gemm_phase(PG8_LAS unsigned char* lds, const Gemm g, const StaticOrder& S, const Epi& E) {
;     ...
;             PG8_WAIT_V(8); PG8_WAIT_L(0); PG8_BAR; PG8_MMA(1, 0, At, B0); PG8_MMA(1, 1, At, B1); PG8_BAR; PG8_SCHED;
;             PG8_LDB(B0, 1, 0); PG8_LDB(B1, 1, 1); PG8_SCHED; PG8_LDA(At, 1, 0); PG8_STAGE(PG8_SA(0, 1), a2 + hstepA, voffA);
;             PG8_WAIT_V(8); PG8_WAIT_L(0); PG8_BAR; PG8_MMA(0, 0, At, B0); PG8_MMA(0, 1, At, B1); PG8_BAR; PG8_SCHED;
.Lrw_p9_1_d:
	s_waitcnt lgkmcnt(0)
	s_barrier
	s_setprio 1
	s_waitcnt lgkmcnt(0)
	v_mfma_f32_16x16x32_bf16 v[62:65], v[132:135], v[206:209], v[62:65]
	v_mfma_f32_16x16x32_bf16 v[58:61], v[182:185], v[206:209], v[58:61]
	v_mfma_f32_16x16x32_bf16 v[54:57], v[132:135], v[214:217], v[54:57]
	v_mfma_f32_16x16x32_bf16 v[50:53], v[182:185], v[214:217], v[50:53]
	v_mfma_f32_16x16x32_bf16 v[46:49], v[132:135], v[222:225], v[46:49]
	v_mfma_f32_16x16x32_bf16 v[42:45], v[182:185], v[222:225], v[42:45]
	v_mfma_f32_16x16x32_bf16 v[38:41], v[132:135], v[230:233], v[38:41]
	v_mfma_f32_16x16x32_bf16 v[34:37], v[182:185], v[230:233], v[34:37]
	v_mfma_f32_16x16x32_bf16 v[62:65], v[178:181], v[210:213], v[62:65]
	v_mfma_f32_16x16x32_bf16 v[58:61], v[186:189], v[210:213], v[58:61]
	v_mfma_f32_16x16x32_bf16 v[54:57], v[178:181], v[218:221], v[54:57]
	v_mfma_f32_16x16x32_bf16 v[50:53], v[186:189], v[218:221], v[50:53]
	v_mfma_f32_16x16x32_bf16 v[46:49], v[178:181], v[226:229], v[46:49]
	v_mfma_f32_16x16x32_bf16 v[42:45], v[186:189], v[226:229], v[42:45]
	v_mfma_f32_16x16x32_bf16 v[38:41], v[178:181], v[234:237], v[38:41]
	v_mfma_f32_16x16x32_bf16 v[34:37], v[186:189], v[234:237], v[34:37]
	s_setprio 0
	s_setprio 1
	v_mfma_f32_16x16x32_bf16 v[30:33], v[190:193], v[206:209], v[30:33]
	v_mfma_f32_16x16x32_bf16 v[26:29], v[198:201], v[206:209], v[26:29]
	v_mfma_f32_16x16x32_bf16 v[22:25], v[190:193], v[214:217], v[22:25]
	v_mfma_f32_16x16x32_bf16 v[18:21], v[198:201], v[214:217], v[18:21]
	v_mfma_f32_16x16x32_bf16 v[14:17], v[190:193], v[222:225], v[14:17]
	v_mfma_f32_16x16x32_bf16 v[10:13], v[198:201], v[222:225], v[10:13]
	v_mfma_f32_16x16x32_bf16 v[6:9], v[190:193], v[230:233], v[6:9]
	v_mfma_f32_16x16x32_bf16 v[2:5], v[198:201], v[230:233], v[2:5]
	v_mfma_f32_16x16x32_bf16 v[30:33], v[194:197], v[210:213], v[30:33]
	v_mfma_f32_16x16x32_bf16 v[26:29], v[202:205], v[210:213], v[26:29]
	v_mfma_f32_16x16x32_bf16 v[22:25], v[194:197], v[218:221], v[22:25]
	v_mfma_f32_16x16x32_bf16 v[18:21], v[202:205], v[218:221], v[18:21]
	v_mfma_f32_16x16x32_bf16 v[14:17], v[194:197], v[226:229], v[14:17]
	v_mfma_f32_16x16x32_bf16 v[10:13], v[202:205], v[226:229], v[10:13]
	v_mfma_f32_16x16x32_bf16 v[6:9], v[194:197], v[234:237], v[6:9]
	v_mfma_f32_16x16x32_bf16 v[2:5], v[202:205], v[234:237], v[2:5]
	s_setprio 0
	s_barrier
	s_add_i32 s84, 0, 0x18000
	s_add_i32 s85, 0, 0x1c000
	ds_read_b128 v[132:135], v251 offset:32768
	ds_read_b128 v[178:181], v251 offset:33792
	ds_read_b128 v[182:185], v251 offset:34816
	ds_read_b128 v[186:189], v251 offset:35840
	ds_read_b128 v[190:193], v251 offset:49152
	ds_read_b128 v[194:197], v251 offset:50176
	ds_read_b128 v[198:201], v251 offset:51200
	ds_read_b128 v[202:205], v251 offset:52224
	s_mov_b32 m0, s68
	ds_read_b128 v[206:209], v176 offset:32768
	ds_read_b128 v[210:213], v176 offset:33792
	ds_read_b128 v[214:217], v176 offset:34816
	ds_read_b128 v[218:221], v176 offset:35840
	ds_read_b128 v[222:225], v176 offset:36864
	ds_read_b128 v[226:229], v176 offset:37888
	ds_read_b128 v[230:233], v176 offset:38912
	ds_read_b128 v[234:237], v176 offset:39936
	global_load_lds_dwordx4 v245, s[100:101]
	s_mov_b32 m0, s69
	s_nop 0
	global_load_lds_dwordx4 v246, s[100:101]
	s_waitcnt vmcnt(8)
	s_waitcnt lgkmcnt(0)
	s_barrier
	s_setprio 1
	s_waitcnt lgkmcnt(0)
	v_mfma_f32_16x16x32_bf16 v[126:129], v[132:135], v[206:209], v[126:129]
	v_mfma_f32_16x16x32_bf16 v[122:125], v[182:185], v[206:209], v[122:125]
	v_mfma_f32_16x16x32_bf16 v[118:121], v[132:135], v[214:217], v[118:121]
	v_mfma_f32_16x16x32_bf16 v[114:117], v[182:185], v[214:217], v[114:117]
	v_mfma_f32_16x16x32_bf16 v[110:113], v[132:135], v[222:225], v[110:113]
	v_mfma_f32_16x16x32_bf16 v[106:109], v[182:185], v[222:225], v[106:109]
	v_mfma_f32_16x16x32_bf16 v[102:105], v[132:135], v[230:233], v[102:105]
	v_mfma_f32_16x16x32_bf16 v[98:101], v[182:185], v[230:233], v[98:101]
	v_mfma_f32_16x16x32_bf16 v[126:129], v[178:181], v[210:213], v[126:129]
	v_mfma_f32_16x16x32_bf16 v[122:125], v[186:189], v[210:213], v[122:125]
	v_mfma_f32_16x16x32_bf16 v[118:121], v[178:181], v[218:221], v[118:121]
	v_mfma_f32_16x16x32_bf16 v[114:117], v[186:189], v[218:221], v[114:117]
	v_mfma_f32_16x16x32_bf16 v[110:113], v[178:181], v[226:229], v[110:113]
	v_mfma_f32_16x16x32_bf16 v[106:109], v[186:189], v[226:229], v[106:109]
	v_mfma_f32_16x16x32_bf16 v[102:105], v[178:181], v[234:237], v[102:105]
	v_mfma_f32_16x16x32_bf16 v[98:101], v[186:189], v[234:237], v[98:101]
	s_setprio 0
	s_setprio 1
	v_mfma_f32_16x16x32_bf16 v[94:97], v[190:193], v[206:209], v[94:97]
	v_mfma_f32_16x16x32_bf16 v[90:93], v[198:201], v[206:209], v[90:93]
	v_mfma_f32_16x16x32_bf16 v[86:89], v[190:193], v[214:217], v[86:89]
	v_mfma_f32_16x16x32_bf16 v[82:85], v[198:201], v[214:217], v[82:85]
	v_mfma_f32_16x16x32_bf16 v[78:81], v[190:193], v[222:225], v[78:81]
	v_mfma_f32_16x16x32_bf16 v[74:77], v[198:201], v[222:225], v[74:77]
	v_mfma_f32_16x16x32_bf16 v[70:73], v[190:193], v[230:233], v[70:73]
	v_mfma_f32_16x16x32_bf16 v[66:69], v[198:201], v[230:233], v[66:69]
	v_mfma_f32_16x16x32_bf16 v[94:97], v[194:197], v[210:213], v[94:97]
	v_mfma_f32_16x16x32_bf16 v[90:93], v[202:205], v[210:213], v[90:93]
	v_mfma_f32_16x16x32_bf16 v[86:89], v[194:197], v[218:221], v[86:89]
	v_mfma_f32_16x16x32_bf16 v[82:85], v[202:205], v[218:221], v[82:85]
	v_mfma_f32_16x16x32_bf16 v[78:81], v[194:197], v[226:229], v[78:81]
	v_mfma_f32_16x16x32_bf16 v[74:77], v[202:205], v[226:229], v[74:77]
	v_mfma_f32_16x16x32_bf16 v[70:73], v[194:197], v[234:237], v[70:73]
	v_mfma_f32_16x16x32_bf16 v[66:69], v[202:205], v[234:237], v[66:69]
	s_setprio 0
	s_barrier
; #define PG8_STAGE(bufoff, gbase, voff) do { _Pragma("unroll") for (int _i = 0; _i < 2; ++_i) \
;         __builtin_amdgcn_global_load_lds((const unsigned*)((const char*)(gbase) + (voff)[_i]), (PG8_LAS unsigned*)(lds + (bufoff) + ldsw + _i * 8192), 16, 0, 0); } while (0)
; #define PG8_LDA(dst, b, h) do { _Pragma("unroll") for (int m = 0; m < 4; ++m) _Pragma("unroll") for (int k = 0; k < 2; ++k) dst[m][k] = *(const PG8_LAS bf16x8*)(lds + PG8_SA(b, h) + aoff + m * 2048 + k * 1024); } while (0)
; #define PG8_MMA(ai, bj, At, Bt) do { __builtin_amdgcn_s_setprio(1); _Pragma("unroll") for (int m = 0; m < 4; ++m) _Pragma("unroll") for (int n = 0; n < 2; ++n) _Pragma("unroll") for (int k = 0; k < 2; ++k) \
;         acc[ai][bj][m][n] = __builtin_amdgcn_mfma_f32_16x16x32_bf16(Bt[n][k], At[m][k], acc[ai][bj][m][n], 0, 0, 0); __builtin_amdgcn_s_setprio(0); } while (0)
; #define PG8_WAIT_V(n) asm volatile("s_waitcnt vmcnt(" #n ")" ::: "memory")
; #define PG8_WAIT_L(n) asm volatile("s_waitcnt lgkmcnt(" #n ")" ::: "memory")
; #define PG8_BAR __builtin_amdgcn_s_barrier()
; #define PG8_SCHED __builtin_amdgcn_sched_barrier(0)
; template <class Epi, bool ALIGN_EPI, bool ABLK = false>
; __device__ __forceinline__ void gemm_phase(PG8_LAS unsigned char* lds, const Gemm g, const StaticOrder& S, const Epi& E) {
;     ...
;             PG8_LDA(At, 1, 1); PG8_STAGE(PG8_SB(1, 0), b3, voffB); PG8_STAGE(PG8_SB(1, 1), b3 + hstepB, voffB); PG8_STAGE(PG8_SA(1, 0), a3, voffA);
;             PG8_WAIT_V(8); PG8_WAIT_L(0); PG8_BAR; PG8_MMA(1, 0, At, B0); PG8_MMA(1, 1, At, B1); PG8_BAR; PG8_SCHED;
;         }
	s_add_i32 s84, s84, s9
	s_add_u32 s60, s60, s28
	s_addc_u32 s61, s61, s29
	s_mov_b32 m0, s84
	ds_read_b128 v[206:209], v176 offset:49152
	ds_read_b128 v[210:213], v176 offset:50176
	ds_read_b128 v[214:217], v176 offset:51200
	ds_read_b128 v[218:221], v176 offset:52224
	ds_read_b128 v[222:225], v176 offset:53248
	ds_read_b128 v[226:229], v176 offset:54272
	ds_read_b128 v[230:233], v176 offset:55296
	ds_read_b128 v[234:237], v176 offset:56320
	global_load_lds_dwordx4 v140, s[60:61]
	s_add_i32 m0, s84, 0x2000
	s_add_i32 s84, s85, s9
	global_load_lds_dwordx4 v142, s[60:61]
	s_add_u32 s60, s60, 0x40000
	s_addc_u32 s61, s61, 0
	s_mov_b32 m0, s84
	s_nop 0
	global_load_lds_dwordx4 v140, s[60:61]
	s_add_i32 m0, s84, 0x2000
	s_nop 0
	global_load_lds_dwordx4 v142, s[60:61]
	s_mov_b32 m0, s70
	s_nop 0
	global_load_lds_dwordx4 v247, s[100:101]
	s_mov_b32 m0, s72
	s_nop 0
	global_load_lds_dwordx4 v248, s[100:101]
	s_waitcnt vmcnt(8)
	s_waitcnt lgkmcnt(0)
	s_barrier
	s_setprio 1
	s_waitcnt lgkmcnt(0)
	v_mfma_f32_16x16x32_bf16 v[62:65], v[132:135], v[206:209], v[62:65]
	v_mfma_f32_16x16x32_bf16 v[58:61], v[182:185], v[206:209], v[58:61]
	v_mfma_f32_16x16x32_bf16 v[54:57], v[132:135], v[214:217], v[54:57]
	v_mfma_f32_16x16x32_bf16 v[50:53], v[182:185], v[214:217], v[50:53]
	v_mfma_f32_16x16x32_bf16 v[46:49], v[132:135], v[222:225], v[46:49]
	v_mfma_f32_16x16x32_bf16 v[42:45], v[182:185], v[222:225], v[42:45]
	v_mfma_f32_16x16x32_bf16 v[38:41], v[132:135], v[230:233], v[38:41]
	v_mfma_f32_16x16x32_bf16 v[34:37], v[182:185], v[230:233], v[34:37]
	v_mfma_f32_16x16x32_bf16 v[62:65], v[178:181], v[210:213], v[62:65]
	v_mfma_f32_16x16x32_bf16 v[58:61], v[186:189], v[210:213], v[58:61]
	v_mfma_f32_16x16x32_bf16 v[54:57], v[178:181], v[218:221], v[54:57]
	v_mfma_f32_16x16x32_bf16 v[50:53], v[186:189], v[218:221], v[50:53]
	v_mfma_f32_16x16x32_bf16 v[46:49], v[178:181], v[226:229], v[46:49]
	v_mfma_f32_16x16x32_bf16 v[42:45], v[186:189], v[226:229], v[42:45]
	v_mfma_f32_16x16x32_bf16 v[38:41], v[178:181], v[234:237], v[38:41]
	v_mfma_f32_16x16x32_bf16 v[34:37], v[186:189], v[234:237], v[34:37]
	s_setprio 0
	s_setprio 1
	v_mfma_f32_16x16x32_bf16 v[30:33], v[190:193], v[206:209], v[30:33]
	v_mfma_f32_16x16x32_bf16 v[26:29], v[198:201], v[206:209], v[26:29]
	v_mfma_f32_16x16x32_bf16 v[22:25], v[190:193], v[214:217], v[22:25]
	v_mfma_f32_16x16x32_bf16 v[18:21], v[198:201], v[214:217], v[18:21]
	v_mfma_f32_16x16x32_bf16 v[14:17], v[190:193], v[222:225], v[14:17]
	v_mfma_f32_16x16x32_bf16 v[10:13], v[198:201], v[222:225], v[10:13]
	v_mfma_f32_16x16x32_bf16 v[6:9], v[190:193], v[230:233], v[6:9]
	v_mfma_f32_16x16x32_bf16 v[2:5], v[198:201], v[230:233], v[2:5]
	v_mfma_f32_16x16x32_bf16 v[30:33], v[194:197], v[210:213], v[30:33]
	v_mfma_f32_16x16x32_bf16 v[26:29], v[202:205], v[210:213], v[26:29]
	v_mfma_f32_16x16x32_bf16 v[22:25], v[194:197], v[218:221], v[22:25]
	v_mfma_f32_16x16x32_bf16 v[18:21], v[202:205], v[218:221], v[18:21]
	v_mfma_f32_16x16x32_bf16 v[14:17], v[194:197], v[226:229], v[14:17]
	v_mfma_f32_16x16x32_bf16 v[10:13], v[202:205], v[226:229], v[10:13]
	v_mfma_f32_16x16x32_bf16 v[6:9], v[194:197], v[234:237], v[6:9]
	v_mfma_f32_16x16x32_bf16 v[2:5], v[202:205], v[234:237], v[2:5]
	s_setprio 0
	s_barrier
	s_add_i32 s83, s83, 2
	s_add_u32 s81, s81, 0x100
	s_addc_u32 s82, s82, 0
	s_add_u32 s58, s58, 0x10000
	s_addc_u32 s59, s59, 0
	s_cmp_gt_u32 s83, 13
	s_cbranch_scc0 .LBB0_2495
	s_and_b64 vcc, exec, s[36:37]
	s_cbranch_vccz .LBB0_2498
	s_barrier
